# v25 + gates epilogue: sqrt sequence without the never-taken denormal scaling and class select (bit-identical)
# speedup vs baseline: 1.0163x; 1.0027x over previous
; #define PG8_STAGE(bufoff, gbase, voff) do { _Pragma("unroll") for (int _i = 0; _i < 2; ++_i) \
;         __builtin_amdgcn_global_load_lds((const unsigned*)((const char*)(gbase) + (voff)[_i]), (LAS unsigned*)(lds + (bufoff) + ldsw + _i * 8192), 16, 0, 0); } while (0)
; #define PG8_LDA(dst, b, h) do { _Pragma("unroll") for (int m = 0; m < 4; ++m) _Pragma("unroll") for (int k = 0; k < 2; ++k) dst[m][k] = *(const LAS bf16x8*)(lds + PG8_SA(b, h) + aoff + m * 2048 + k * 1024); } while (0)
; #define PG8_LDB(dst, b, h) do { _Pragma("unroll") for (int n = 0; n < 2; ++n) _Pragma("unroll") for (int k = 0; k < 2; ++k) dst[n][k] = *(const LAS bf16x8*)(lds + PG8_SB(b, h) + boff + n * 2048 + k * 1024); } while (0)
; #define PG8_WAIT_V(n) asm volatile("s_waitcnt vmcnt(" #n ")" ::: "memory")
; #define PG8_WAIT_L(n) asm volatile("s_waitcnt lgkmcnt(" #n ")" ::: "memory")
; #define PG8_BAR __builtin_amdgcn_s_barrier()
; #define PG8_SCHED __builtin_amdgcn_sched_barrier(0)
; template <class Epi>
; __device__ __forceinline__ void gemm_phase(LAS unsigned char* lds, const Gemm g, const StaticOrder& S, const Epi& E) {
;     ...
;         const bool has_next = S.next(ui + 1, nxt);
;         const char* nA = has_next ? (const char*)g.A + (size_t)nxt.pm * tstepA + (size_t)(nxt.pn >> g.a_shift) * g.a_step : cA; const char* nB = has_next ? (const char*)g.Bt + (size_t)nxt.pn * tstepB : cB;
;         for (int t = 0; t < nt; t += 2) {
;             const bool last = (t == nt - 2);
;             const char* a1 = cA + (size_t)(t + 1) * kstep;
;             const char* a2 = last ? nA : cA + (size_t)(t + 2) * kstep; const char* b2 = last ? nB : cB + (size_t)(t + 2) * kstep;
;             const char* a3 = a2 + kstep; const char* b3 = b2 + kstep;
;             PG8_LDB(B0, 0, 0); PG8_SCHED; PG8_LDA(At, 0, 0); PG8_STAGE(PG8_SA(1, 1), a1 + hstepA, voffA);
;             PG8_WAIT_L(8); PG8_BAR; PG8_WAIT_L(0); PG8_MMA(0, 0, At, B0); PG8_BAR; PG8_SCHED;
;             PG8_LDB(B1, 0, 1); PG8_STAGE(PG8_SB(0, 0), b2, voffB);
;             PG8_BAR; PG8_WAIT_L(0); PG8_MMA(0, 1, At, B1); PG8_BAR;
;             PG8_LDA(At, 0, 1); PG8_STAGE(PG8_SA(0, 0), a2, voffA);
;             PG8_BAR; PG8_WAIT_L(0); PG8_MMA(1, 0, At, B0); PG8_BAR; PG8_SCHED;
;             PG8_STAGE(PG8_SB(0, 1), b2 + hstepB, voffB);
;             PG8_WAIT_V(6); PG8_BAR; PG8_MMA(1, 1, At, B1); PG8_BAR;
.LBB0_1094:
	s_ashr_i32 s41, s40, 31
	s_lshl_b64 s[42:43], s[40:41], 19
	s_add_u32 s39, s18, s42
	s_addc_u32 s41, s19, s43
	s_ashr_i32 s42, s38, 1
	s_ashr_i32 s43, s42, 31
	s_lshl_b64 s[42:43], s[42:43], 9
	s_add_u32 s42, s39, s42
	v_cmp_lt_i64_e32 vcc, s[36:37], v[176:177]
	s_addc_u32 s43, s41, s43
	ds_read_b128 v[0:3], v207
	ds_read_b128 v[4:7], v207 offset:1024
	ds_read_b128 v[8:11], v207 offset:2048
	ds_read_b128 v[12:15], v207 offset:3072
	s_and_b64 s[44:45], vcc, exec
	s_cselect_b32 s49, s43, s15
	s_cselect_b32 s48, s42, s14
	s_ashr_i32 s39, s38, 31
	s_lshl_b64 s[44:45], s[38:39], 17
	s_add_u32 s44, s5, s44
	s_addc_u32 s45, s6, s45
	s_and_b64 s[46:47], vcc, exec
	s_cselect_b32 s47, s45, s17
	s_cselect_b32 s46, s44, s16
	s_add_u32 s82, s14, 0x40080
	s_addc_u32 s83, s15, 0
	s_add_i32 s85, s8, 0xc000
	v_lshl_add_u64 v[48:49], s[82:83], 0, v[168:169]
	s_mov_b32 m0, s85
	s_add_i32 s39, s8, 0xe000
	ds_read_b128 v[16:19], v208
	ds_read_b128 v[20:23], v208 offset:1024
	ds_read_b128 v[24:27], v208 offset:2048
	ds_read_b128 v[28:31], v208 offset:3072
	ds_read_b128 v[32:35], v208 offset:4096
	ds_read_b128 v[36:39], v208 offset:5120
	ds_read_b128 v[40:43], v208 offset:6144
	ds_read_b128 v[44:47], v208 offset:7168
	global_load_lds_dwordx4 v[48:49], off
	v_lshl_add_u64 v[48:49], s[82:83], 0, v[172:173]
	s_mov_b32 m0, s39
	s_nop 0
	global_load_lds_dwordx4 v[48:49], off
	s_waitcnt lgkmcnt(8)
	s_barrier
	s_waitcnt lgkmcnt(0)
	s_setprio 1
	s_waitcnt lgkmcnt(0)
	v_mfma_f32_16x16x32_bf16 v[48:51], v[0:3], v[16:19], 0
	v_mfma_f32_16x16x32_bf16 v[52:55], v[8:11], v[16:19], 0
	v_mfma_f32_16x16x32_bf16 v[56:59], v[0:3], v[24:27], 0
	v_mfma_f32_16x16x32_bf16 v[60:63], v[8:11], v[24:27], 0
	v_mfma_f32_16x16x32_bf16 v[64:67], v[0:3], v[32:35], 0
	v_mfma_f32_16x16x32_bf16 v[68:71], v[8:11], v[32:35], 0
	v_mfma_f32_16x16x32_bf16 v[72:75], v[0:3], v[40:43], 0
	v_mfma_f32_16x16x32_bf16 v[76:79], v[8:11], v[40:43], 0
	v_mfma_f32_16x16x32_bf16 v[48:51], v[4:7], v[20:23], v[48:51]
	v_mfma_f32_16x16x32_bf16 v[52:55], v[12:15], v[20:23], v[52:55]
	v_mfma_f32_16x16x32_bf16 v[56:59], v[4:7], v[28:31], v[56:59]
	v_mfma_f32_16x16x32_bf16 v[60:63], v[12:15], v[28:31], v[60:63]
	v_mfma_f32_16x16x32_bf16 v[64:67], v[4:7], v[36:39], v[64:67]
	v_mfma_f32_16x16x32_bf16 v[68:71], v[12:15], v[36:39], v[68:71]
	v_mfma_f32_16x16x32_bf16 v[72:75], v[4:7], v[44:47], v[72:75]
	v_mfma_f32_16x16x32_bf16 v[76:79], v[12:15], v[44:47], v[76:79]
	s_setprio 0
	s_barrier
	v_lshl_add_u64 v[212:213], s[16:17], 0, v[170:171]
	s_add_i32 s82, s75, s7
	v_lshl_add_u64 v[96:97], v[212:213], 0, s[28:29]
	s_mov_b32 m0, s82
	v_lshl_add_u64 v[214:215], s[16:17], 0, v[174:175]
	s_add_i32 s41, s82, 0x2000
	ds_read_b128 v[80:83], v209
	ds_read_b128 v[84:87], v209 offset:1024
	ds_read_b128 v[88:91], v209 offset:2048
	ds_read_b128 v[92:95], v209 offset:3072
	global_load_lds_dwordx4 v[96:97], off
	v_lshl_add_u64 v[96:97], v[214:215], 0, s[28:29]
	s_mov_b32 m0, s41
	s_nop 0
	global_load_lds_dwordx4 v[96:97], off
	s_barrier
	s_waitcnt lgkmcnt(0)
	s_setprio 1
	s_waitcnt lgkmcnt(0)
	v_mfma_f32_16x16x32_bf16 v[96:99], v[80:83], v[16:19], 0
	v_mfma_f32_16x16x32_bf16 v[16:19], v[88:91], v[16:19], 0
	v_mfma_f32_16x16x32_bf16 v[96:99], v[84:87], v[20:23], v[96:99]
	v_mfma_f32_16x16x32_bf16 v[16:19], v[92:95], v[20:23], v[16:19]
	v_mfma_f32_16x16x32_bf16 v[20:23], v[80:83], v[24:27], 0
	v_mfma_f32_16x16x32_bf16 v[24:27], v[88:91], v[24:27], 0
	v_mfma_f32_16x16x32_bf16 v[20:23], v[84:87], v[28:31], v[20:23]
	v_mfma_f32_16x16x32_bf16 v[24:27], v[92:95], v[28:31], v[24:27]
	v_mfma_f32_16x16x32_bf16 v[28:31], v[80:83], v[32:35], 0
	v_mfma_f32_16x16x32_bf16 v[32:35], v[88:91], v[32:35], 0
	v_mfma_f32_16x16x32_bf16 v[28:31], v[84:87], v[36:39], v[28:31]
	v_mfma_f32_16x16x32_bf16 v[32:35], v[92:95], v[36:39], v[32:35]
	v_mfma_f32_16x16x32_bf16 v[36:39], v[80:83], v[40:43], 0
	v_mfma_f32_16x16x32_bf16 v[40:43], v[88:91], v[40:43], 0
	v_mfma_f32_16x16x32_bf16 v[36:39], v[84:87], v[44:47], v[36:39]
	v_mfma_f32_16x16x32_bf16 v[40:43], v[92:95], v[44:47], v[40:43]
	s_setprio 0
	v_lshl_add_u64 v[216:217], s[14:15], 0, v[168:169]
	s_mov_b32 m0, s8
	v_lshl_add_u64 v[128:129], v[216:217], 0, s[28:29]
	v_lshl_add_u64 v[220:221], s[14:15], 0, v[172:173]
	s_barrier
	ds_read_b128 v[44:47], v208 offset:16384
	ds_read_b128 v[100:103], v208 offset:17408
	ds_read_b128 v[104:107], v208 offset:18432
	ds_read_b128 v[108:111], v208 offset:19456
	ds_read_b128 v[112:115], v208 offset:20480
	ds_read_b128 v[116:119], v208 offset:21504
	ds_read_b128 v[120:123], v208 offset:22528
	ds_read_b128 v[124:127], v208 offset:23552
	global_load_lds_dwordx4 v[128:129], off
	v_lshl_add_u64 v[128:129], v[220:221], 0, s[28:29]
	s_mov_b32 m0, s9
	s_nop 0
	global_load_lds_dwordx4 v[128:129], off
	s_barrier
	s_waitcnt lgkmcnt(0)
	s_setprio 1
	s_waitcnt lgkmcnt(0)
	v_mfma_f32_16x16x32_bf16 v[128:131], v[0:3], v[44:47], 0
	v_mfma_f32_16x16x32_bf16 v[136:139], v[0:3], v[104:107], 0
	v_mfma_f32_16x16x32_bf16 v[144:147], v[0:3], v[112:115], 0
	v_mfma_f32_16x16x32_bf16 v[0:3], v[0:3], v[120:123], 0
	v_mfma_f32_16x16x32_bf16 v[128:131], v[4:7], v[100:103], v[128:131]
	v_mfma_f32_16x16x32_bf16 v[132:135], v[8:11], v[44:47], 0
	v_mfma_f32_16x16x32_bf16 v[136:139], v[4:7], v[108:111], v[136:139]
	v_mfma_f32_16x16x32_bf16 v[140:143], v[8:11], v[104:107], 0
	v_mfma_f32_16x16x32_bf16 v[144:147], v[4:7], v[116:119], v[144:147]
	v_mfma_f32_16x16x32_bf16 v[148:151], v[8:11], v[112:115], 0
	v_mfma_f32_16x16x32_bf16 v[0:3], v[4:7], v[124:127], v[0:3]
	v_mfma_f32_16x16x32_bf16 v[4:7], v[8:11], v[120:123], 0
	v_mfma_f32_16x16x32_bf16 v[132:135], v[12:15], v[100:103], v[132:135]
	v_mfma_f32_16x16x32_bf16 v[140:143], v[12:15], v[108:111], v[140:143]
	v_mfma_f32_16x16x32_bf16 v[148:151], v[12:15], v[116:119], v[148:151]
	v_mfma_f32_16x16x32_bf16 v[4:7], v[12:15], v[124:127], v[4:7]
	s_setprio 0
	s_barrier
; #define PG8_STAGE(bufoff, gbase, voff) do { _Pragma("unroll") for (int _i = 0; _i < 2; ++_i) \
;         __builtin_amdgcn_global_load_lds((const unsigned*)((const char*)(gbase) + (voff)[_i]), (LAS unsigned*)(lds + (bufoff) + ldsw + _i * 8192), 16, 0, 0); } while (0)
; #define PG8_LDA(dst, b, h) do { _Pragma("unroll") for (int m = 0; m < 4; ++m) _Pragma("unroll") for (int k = 0; k < 2; ++k) dst[m][k] = *(const LAS bf16x8*)(lds + PG8_SA(b, h) + aoff + m * 2048 + k * 1024); } while (0)
; #define PG8_LDB(dst, b, h) do { _Pragma("unroll") for (int n = 0; n < 2; ++n) _Pragma("unroll") for (int k = 0; k < 2; ++k) dst[n][k] = *(const LAS bf16x8*)(lds + PG8_SB(b, h) + boff + n * 2048 + k * 1024); } while (0)
; #define PG8_MMA(ai, bj, At, Bt) do { __builtin_amdgcn_s_setprio(1); _Pragma("unroll") for (int m = 0; m < 4; ++m) _Pragma("unroll") for (int n = 0; n < 2; ++n) _Pragma("unroll") for (int k = 0; k < 2; ++k) \
;         acc[ai][bj][m][n] = __builtin_amdgcn_mfma_f32_16x16x32_bf16(Bt[n][k], At[m][k], acc[ai][bj][m][n], 0, 0, 0); __builtin_amdgcn_s_setprio(0); } while (0)
; #define PG8_WAIT_V(n) asm volatile("s_waitcnt vmcnt(" #n ")" ::: "memory")
; #define PG8_WAIT_L(n) asm volatile("s_waitcnt lgkmcnt(" #n ")" ::: "memory")
; #define PG8_BAR __builtin_amdgcn_s_barrier()
; #define PG8_SCHED __builtin_amdgcn_sched_barrier(0)
; template <class Epi>
; __device__ __forceinline__ void gemm_phase(LAS unsigned char* lds, const Gemm g, const StaticOrder& S, const Epi& E) {
;     ...
;             PG8_STAGE(PG8_SB(0, 1), b2 + hstepB, voffB);
;             PG8_WAIT_V(6); PG8_BAR; PG8_MMA(1, 1, At, B1); PG8_BAR;
;             PG8_LDB(B0, 1, 0); PG8_SCHED; PG8_LDA(At, 1, 0); PG8_STAGE(PG8_SA(0, 1), a2 + hstepA, voffA);
;             PG8_WAIT_L(8); PG8_BAR; PG8_WAIT_L(0); PG8_MMA(0, 0, At, B0); PG8_BAR; PG8_SCHED;
;             PG8_LDB(B1, 1, 1); PG8_STAGE(PG8_SB(1, 0), b3, voffB);
;             PG8_BAR; PG8_WAIT_L(0); PG8_MMA(0, 1, At, B1); PG8_BAR;
;             PG8_LDA(At, 1, 1); PG8_STAGE(PG8_SA(1, 0), a3, voffA);
	s_add_u32 s86, s16, 0x10100
	s_addc_u32 s87, s17, 0
	s_add_i32 s83, s76, s7
	v_lshl_add_u64 v[8:9], s[86:87], 0, v[170:171]
	s_mov_b32 m0, s83
	s_add_i32 s81, s83, 0x2000
	global_load_lds_dwordx4 v[8:9], off
	v_lshl_add_u64 v[8:9], s[86:87], 0, v[174:175]
	s_mov_b32 m0, s81
	s_nop 0
	global_load_lds_dwordx4 v[8:9], off
	s_waitcnt vmcnt(6)
	s_barrier
	s_setprio 1
	v_mfma_f32_16x16x32_bf16 v[8:11], v[80:83], v[44:47], 0
	v_mfma_f32_16x16x32_bf16 v[12:15], v[88:91], v[44:47], 0
	v_mfma_f32_16x16x32_bf16 v[8:11], v[84:87], v[100:103], v[8:11]
	v_mfma_f32_16x16x32_bf16 v[12:15], v[92:95], v[100:103], v[12:15]
	v_mfma_f32_16x16x32_bf16 v[44:47], v[80:83], v[104:107], 0
	v_mfma_f32_16x16x32_bf16 v[100:103], v[88:91], v[104:107], 0
	v_mfma_f32_16x16x32_bf16 v[104:107], v[80:83], v[112:115], 0
	v_mfma_f32_16x16x32_bf16 v[80:83], v[80:83], v[120:123], 0
	v_mfma_f32_16x16x32_bf16 v[44:47], v[84:87], v[108:111], v[44:47]
	v_mfma_f32_16x16x32_bf16 v[100:103], v[92:95], v[108:111], v[100:103]
	v_mfma_f32_16x16x32_bf16 v[104:107], v[84:87], v[116:119], v[104:107]
	v_mfma_f32_16x16x32_bf16 v[108:111], v[88:91], v[112:115], 0
	v_mfma_f32_16x16x32_bf16 v[80:83], v[84:87], v[124:127], v[80:83]
	v_mfma_f32_16x16x32_bf16 v[84:87], v[88:91], v[120:123], 0
	v_mfma_f32_16x16x32_bf16 v[108:111], v[92:95], v[116:119], v[108:111]
	v_mfma_f32_16x16x32_bf16 v[84:87], v[92:95], v[124:127], v[84:87]
	s_setprio 0
	s_add_i32 s84, 0, 0x18000
	v_add_u32_e32 v218, s84, v205
	s_barrier
	ds_read_b128 v[88:91], v218
	ds_read_b128 v[92:95], v218 offset:1024
	ds_read_b128 v[112:115], v218 offset:2048
	ds_read_b128 v[116:119], v218 offset:3072
	s_add_u32 s86, s14, 0x40100
	s_addc_u32 s87, s15, 0
	s_mov_b32 m0, s35
	v_lshl_add_u64 v[188:189], s[86:87], 0, v[168:169]
	ds_read_b128 v[120:123], v208 offset:32768
	ds_read_b128 v[124:127], v208 offset:33792
	ds_read_b128 v[152:155], v208 offset:34816
	ds_read_b128 v[156:159], v208 offset:35840
	ds_read_b128 v[160:163], v208 offset:36864
	ds_read_b128 v[164:167], v208 offset:37888
	ds_read_b128 v[180:183], v208 offset:38912
	ds_read_b128 v[184:187], v208 offset:39936
	global_load_lds_dwordx4 v[188:189], off
	v_lshl_add_u64 v[188:189], s[86:87], 0, v[172:173]
	s_mov_b32 m0, s63
	s_nop 0
	global_load_lds_dwordx4 v[188:189], off
	s_waitcnt lgkmcnt(8)
	s_barrier
	s_waitcnt lgkmcnt(0)
	s_setprio 1
	s_waitcnt lgkmcnt(0)
	v_mfma_f32_16x16x32_bf16 v[48:51], v[88:91], v[120:123], v[48:51]
	v_mfma_f32_16x16x32_bf16 v[52:55], v[112:115], v[120:123], v[52:55]
	v_mfma_f32_16x16x32_bf16 v[56:59], v[88:91], v[152:155], v[56:59]
	v_mfma_f32_16x16x32_bf16 v[60:63], v[112:115], v[152:155], v[60:63]
	v_mfma_f32_16x16x32_bf16 v[64:67], v[88:91], v[160:163], v[64:67]
	v_mfma_f32_16x16x32_bf16 v[68:71], v[112:115], v[160:163], v[68:71]
	v_mfma_f32_16x16x32_bf16 v[72:75], v[88:91], v[180:183], v[72:75]
	v_mfma_f32_16x16x32_bf16 v[76:79], v[112:115], v[180:183], v[76:79]
	v_mfma_f32_16x16x32_bf16 v[48:51], v[92:95], v[124:127], v[48:51]
	v_mfma_f32_16x16x32_bf16 v[52:55], v[116:119], v[124:127], v[52:55]
	v_mfma_f32_16x16x32_bf16 v[56:59], v[92:95], v[156:159], v[56:59]
	v_mfma_f32_16x16x32_bf16 v[60:63], v[116:119], v[156:159], v[60:63]
	v_mfma_f32_16x16x32_bf16 v[64:67], v[92:95], v[164:167], v[64:67]
	v_mfma_f32_16x16x32_bf16 v[68:71], v[116:119], v[164:167], v[68:71]
	v_mfma_f32_16x16x32_bf16 v[72:75], v[92:95], v[184:187], v[72:75]
	v_mfma_f32_16x16x32_bf16 v[76:79], v[116:119], v[184:187], v[76:79]
	s_setprio 0
	s_barrier
	s_add_i32 s87, 0, 0x1c000
	s_add_i32 s86, s84, s7
	v_add_u32_e32 v235, s87, v205
	v_lshl_add_u64 v[212:213], v[212:213], 0, s[30:31]
	s_mov_b32 m0, s86
	s_add_i32 s84, s86, 0x2000
	ds_read_b128 v[188:191], v235
	ds_read_b128 v[192:195], v235 offset:1024
	ds_read_b128 v[196:199], v235 offset:2048
	ds_read_b128 v[200:203], v235 offset:3072
	global_load_lds_dwordx4 v[212:213], off
	v_lshl_add_u64 v[212:213], v[214:215], 0, s[30:31]
	s_mov_b32 m0, s84
	s_nop 0
	global_load_lds_dwordx4 v[212:213], off
	s_barrier
	s_waitcnt lgkmcnt(0)
	s_setprio 1
	s_waitcnt lgkmcnt(0)
	v_mfma_f32_16x16x32_bf16 v[96:99], v[188:191], v[120:123], v[96:99]
	v_mfma_f32_16x16x32_bf16 v[16:19], v[196:199], v[120:123], v[16:19]
	v_mfma_f32_16x16x32_bf16 v[20:23], v[188:191], v[152:155], v[20:23]
	v_mfma_f32_16x16x32_bf16 v[24:27], v[196:199], v[152:155], v[24:27]
	v_mfma_f32_16x16x32_bf16 v[28:31], v[188:191], v[160:163], v[28:31]
	v_mfma_f32_16x16x32_bf16 v[32:35], v[196:199], v[160:163], v[32:35]
	v_mfma_f32_16x16x32_bf16 v[36:39], v[188:191], v[180:183], v[36:39]
	v_mfma_f32_16x16x32_bf16 v[40:43], v[196:199], v[180:183], v[40:43]
	v_mfma_f32_16x16x32_bf16 v[96:99], v[192:195], v[124:127], v[96:99]
	v_mfma_f32_16x16x32_bf16 v[16:19], v[200:203], v[124:127], v[16:19]
	v_mfma_f32_16x16x32_bf16 v[20:23], v[192:195], v[156:159], v[20:23]
	v_mfma_f32_16x16x32_bf16 v[24:27], v[200:203], v[156:159], v[24:27]
	v_mfma_f32_16x16x32_bf16 v[28:31], v[192:195], v[164:167], v[28:31]
	v_mfma_f32_16x16x32_bf16 v[32:35], v[200:203], v[164:167], v[32:35]
	v_mfma_f32_16x16x32_bf16 v[36:39], v[192:195], v[184:187], v[36:39]
	v_mfma_f32_16x16x32_bf16 v[40:43], v[200:203], v[184:187], v[40:43]
	s_setprio 0
	s_mov_b32 m0, s72
	v_lshl_add_u64 v[212:213], v[216:217], 0, s[30:31]
	s_barrier
	ds_read_b128 v[120:123], v208 offset:49152
	ds_read_b128 v[124:127], v208 offset:50176
	ds_read_b128 v[152:155], v208 offset:51200
	ds_read_b128 v[156:159], v208 offset:52224
	ds_read_b128 v[160:163], v208 offset:53248
	ds_read_b128 v[164:167], v208 offset:54272
	ds_read_b128 v[180:183], v208 offset:55296
	ds_read_b128 v[184:187], v208 offset:56320
	global_load_lds_dwordx4 v[212:213], off
	v_lshl_add_u64 v[212:213], v[220:221], 0, s[30:31]
	s_mov_b32 m0, s73
	s_nop 0
	global_load_lds_dwordx4 v[212:213], off
	s_barrier
; #define PG8_STAGE(bufoff, gbase, voff) do { _Pragma("unroll") for (int _i = 0; _i < 2; ++_i) \
;         __builtin_amdgcn_global_load_lds((const unsigned*)((const char*)(gbase) + (voff)[_i]), (LAS unsigned*)(lds + (bufoff) + ldsw + _i * 8192), 16, 0, 0); } while (0)
; #define PG8_LDA(dst, b, h) do { _Pragma("unroll") for (int m = 0; m < 4; ++m) _Pragma("unroll") for (int k = 0; k < 2; ++k) dst[m][k] = *(const LAS bf16x8*)(lds + PG8_SA(b, h) + aoff + m * 2048 + k * 1024); } while (0)
; #define PG8_LDB(dst, b, h) do { _Pragma("unroll") for (int n = 0; n < 2; ++n) _Pragma("unroll") for (int k = 0; k < 2; ++k) dst[n][k] = *(const LAS bf16x8*)(lds + PG8_SB(b, h) + boff + n * 2048 + k * 1024); } while (0)
; #define PG8_WAIT_V(n) asm volatile("s_waitcnt vmcnt(" #n ")" ::: "memory")
; #define PG8_WAIT_L(n) asm volatile("s_waitcnt lgkmcnt(" #n ")" ::: "memory")
; #define PG8_BAR __builtin_amdgcn_s_barrier()
; #define PG8_SCHED __builtin_amdgcn_sched_barrier(0)
; template <class Epi>
; __device__ __forceinline__ void gemm_phase(LAS unsigned char* lds, const Gemm g, const StaticOrder& S, const Epi& E) {
;     ...
;             PG8_LDB(B0, 0, 0); PG8_SCHED; PG8_LDA(At, 0, 0); PG8_STAGE(PG8_SA(1, 1), a1 + hstepA, voffA);
;             PG8_WAIT_L(8); PG8_BAR; PG8_WAIT_L(0); PG8_MMA(0, 0, At, B0); PG8_BAR; PG8_SCHED;
;             PG8_LDB(B1, 0, 1); PG8_STAGE(PG8_SB(0, 0), b2, voffB);
;             PG8_BAR; PG8_WAIT_L(0); PG8_MMA(0, 1, At, B1); PG8_BAR;
;             PG8_LDA(At, 0, 1); PG8_STAGE(PG8_SA(0, 0), a2, voffA);
;             PG8_BAR; PG8_WAIT_L(0); PG8_MMA(1, 0, At, B0); PG8_BAR; PG8_SCHED;
;             PG8_STAGE(PG8_SB(0, 1), b2 + hstepB, voffB);
;             PG8_WAIT_V(6); PG8_BAR; PG8_MMA(1, 1, At, B1); PG8_BAR;
;             PG8_LDB(B0, 1, 0); PG8_SCHED; PG8_LDA(At, 1, 0); PG8_STAGE(PG8_SA(0, 1), a2 + hstepA, voffA);
;             PG8_WAIT_L(8); PG8_BAR; PG8_WAIT_L(0); PG8_MMA(0, 0, At, B0); PG8_BAR; PG8_SCHED;
;             PG8_LDB(B1, 1, 1); PG8_STAGE(PG8_SB(1, 0), b3, voffB);
;             PG8_BAR; PG8_WAIT_L(0); PG8_MMA(0, 1, At, B1); PG8_BAR;
;             PG8_LDA(At, 1, 1); PG8_STAGE(PG8_SA(1, 0), a3, voffA);
;             PG8_BAR; PG8_WAIT_L(0); PG8_MMA(1, 0, At, B0); PG8_BAR; PG8_SCHED;
;             PG8_STAGE(PG8_SB(1, 1), b3 + hstepB, voffB);
;             PG8_WAIT_V(6); PG8_BAR; PG8_MMA(1, 1, At, B1); PG8_BAR;
	s_waitcnt lgkmcnt(0)
	s_setprio 1
	s_waitcnt lgkmcnt(0)
	v_mfma_f32_16x16x32_bf16 v[128:131], v[88:91], v[120:123], v[128:131]
	v_mfma_f32_16x16x32_bf16 v[132:135], v[112:115], v[120:123], v[132:135]
	v_mfma_f32_16x16x32_bf16 v[136:139], v[88:91], v[152:155], v[136:139]
	v_mfma_f32_16x16x32_bf16 v[140:143], v[112:115], v[152:155], v[140:143]
	v_mfma_f32_16x16x32_bf16 v[144:147], v[88:91], v[160:163], v[144:147]
	v_mfma_f32_16x16x32_bf16 v[148:151], v[112:115], v[160:163], v[148:151]
	v_mfma_f32_16x16x32_bf16 v[0:3], v[88:91], v[180:183], v[0:3]
	v_mfma_f32_16x16x32_bf16 v[4:7], v[112:115], v[180:183], v[4:7]
	v_mfma_f32_16x16x32_bf16 v[128:131], v[92:95], v[124:127], v[128:131]
	v_mfma_f32_16x16x32_bf16 v[132:135], v[116:119], v[124:127], v[132:135]
	v_mfma_f32_16x16x32_bf16 v[136:139], v[92:95], v[156:159], v[136:139]
	v_mfma_f32_16x16x32_bf16 v[140:143], v[116:119], v[156:159], v[140:143]
	v_mfma_f32_16x16x32_bf16 v[144:147], v[92:95], v[164:167], v[144:147]
	v_mfma_f32_16x16x32_bf16 v[148:151], v[116:119], v[164:167], v[148:151]
	v_mfma_f32_16x16x32_bf16 v[0:3], v[92:95], v[184:187], v[0:3]
	v_mfma_f32_16x16x32_bf16 v[4:7], v[116:119], v[184:187], v[4:7]
	s_setprio 0
	s_barrier
	s_add_u32 s88, s16, 0x10180
	s_addc_u32 s89, s17, 0
	s_add_i32 s17, s87, s7
	v_lshl_add_u64 v[88:89], s[88:89], 0, v[170:171]
	s_mov_b32 m0, s17
	s_add_i32 s16, s17, 0x2000
	global_load_lds_dwordx4 v[88:89], off
	v_lshl_add_u64 v[88:89], s[88:89], 0, v[174:175]
	s_mov_b32 m0, s16
	s_nop 0
	global_load_lds_dwordx4 v[88:89], off
	s_waitcnt vmcnt(6)
	s_barrier
	s_setprio 1
	v_mfma_f32_16x16x32_bf16 v[8:11], v[188:191], v[120:123], v[8:11]
	v_mfma_f32_16x16x32_bf16 v[12:15], v[196:199], v[120:123], v[12:15]
	v_mfma_f32_16x16x32_bf16 v[44:47], v[188:191], v[152:155], v[44:47]
	v_mfma_f32_16x16x32_bf16 v[88:91], v[196:199], v[152:155], v[100:103]
	v_mfma_f32_16x16x32_bf16 v[92:95], v[188:191], v[160:163], v[104:107]
	v_mfma_f32_16x16x32_bf16 v[100:103], v[196:199], v[160:163], v[108:111]
	v_mfma_f32_16x16x32_bf16 v[80:83], v[188:191], v[180:183], v[80:83]
	v_mfma_f32_16x16x32_bf16 v[84:87], v[196:199], v[180:183], v[84:87]
	v_mfma_f32_16x16x32_bf16 v[8:11], v[192:195], v[124:127], v[8:11]
	v_mfma_f32_16x16x32_bf16 v[12:15], v[200:203], v[124:127], v[12:15]
	v_mfma_f32_16x16x32_bf16 v[44:47], v[192:195], v[156:159], v[44:47]
	v_mfma_f32_16x16x32_bf16 v[88:91], v[200:203], v[156:159], v[88:91]
	v_mfma_f32_16x16x32_bf16 v[92:95], v[192:195], v[164:167], v[92:95]
	v_mfma_f32_16x16x32_bf16 v[100:103], v[200:203], v[164:167], v[100:103]
	v_mfma_f32_16x16x32_bf16 v[80:83], v[192:195], v[184:187], v[80:83]
	v_mfma_f32_16x16x32_bf16 v[84:87], v[200:203], v[184:187], v[84:87]
	s_setprio 0
	s_barrier
	ds_read_b128 v[104:107], v207
	ds_read_b128 v[108:111], v207 offset:1024
	ds_read_b128 v[112:115], v207 offset:2048
	ds_read_b128 v[116:119], v207 offset:3072
	s_add_u32 s14, s14, 0x40180
	s_addc_u32 s15, s15, 0
	s_mov_b32 m0, s85
	v_lshl_add_u64 v[188:189], s[14:15], 0, v[168:169]
	ds_read_b128 v[120:123], v208
	ds_read_b128 v[124:127], v208 offset:1024
	ds_read_b128 v[152:155], v208 offset:2048
	ds_read_b128 v[156:159], v208 offset:3072
	ds_read_b128 v[160:163], v208 offset:4096
	ds_read_b128 v[164:167], v208 offset:5120
	ds_read_b128 v[180:183], v208 offset:6144
	ds_read_b128 v[184:187], v208 offset:7168
	global_load_lds_dwordx4 v[188:189], off
	v_lshl_add_u64 v[188:189], s[14:15], 0, v[172:173]
	s_mov_b32 m0, s39
	s_nop 0
	global_load_lds_dwordx4 v[188:189], off
	s_waitcnt lgkmcnt(8)
	s_barrier
	s_waitcnt lgkmcnt(0)
	s_setprio 1
	s_waitcnt lgkmcnt(0)
	v_mfma_f32_16x16x32_bf16 v[72:75], v[104:107], v[180:183], v[72:75]
	v_mfma_f32_16x16x32_bf16 v[48:51], v[104:107], v[120:123], v[48:51]
	v_mfma_f32_16x16x32_bf16 v[52:55], v[112:115], v[120:123], v[52:55]
	v_mfma_f32_16x16x32_bf16 v[56:59], v[104:107], v[152:155], v[56:59]
	v_mfma_f32_16x16x32_bf16 v[60:63], v[112:115], v[152:155], v[60:63]
	v_mfma_f32_16x16x32_bf16 v[64:67], v[104:107], v[160:163], v[64:67]
	v_mfma_f32_16x16x32_bf16 v[68:71], v[112:115], v[160:163], v[68:71]
	v_mfma_f32_16x16x32_bf16 v[188:191], v[108:111], v[184:187], v[72:75]
	v_mfma_f32_16x16x32_bf16 v[72:75], v[112:115], v[180:183], v[76:79]
	v_mfma_f32_16x16x32_bf16 v[48:51], v[108:111], v[124:127], v[48:51]
	v_mfma_f32_16x16x32_bf16 v[52:55], v[116:119], v[124:127], v[52:55]
	v_mfma_f32_16x16x32_bf16 v[56:59], v[108:111], v[156:159], v[56:59]
	v_mfma_f32_16x16x32_bf16 v[60:63], v[116:119], v[156:159], v[60:63]
	v_mfma_f32_16x16x32_bf16 v[64:67], v[108:111], v[164:167], v[64:67]
	v_mfma_f32_16x16x32_bf16 v[68:71], v[116:119], v[164:167], v[68:71]
	v_mfma_f32_16x16x32_bf16 v[76:79], v[116:119], v[184:187], v[72:75]
	s_setprio 0
	s_barrier
	s_mov_b32 m0, s82
	v_lshl_add_u64 v[216:217], s[46:47], 0, v[170:171]
	ds_read_b128 v[72:75], v209
	ds_read_b128 v[192:195], v209 offset:1024
	ds_read_b128 v[196:199], v209 offset:2048
	ds_read_b128 v[200:203], v209 offset:3072
	global_load_lds_dwordx4 v[216:217], off
	v_lshl_add_u64 v[232:233], s[46:47], 0, v[174:175]
	s_mov_b32 m0, s41
	s_nop 0
	global_load_lds_dwordx4 v[232:233], off
	s_barrier
; #define PG8_STAGE(bufoff, gbase, voff) do { _Pragma("unroll") for (int _i = 0; _i < 2; ++_i) \
;         __builtin_amdgcn_global_load_lds((const unsigned*)((const char*)(gbase) + (voff)[_i]), (LAS unsigned*)(lds + (bufoff) + ldsw + _i * 8192), 16, 0, 0); } while (0)
; #define PG8_LDA(dst, b, h) do { _Pragma("unroll") for (int m = 0; m < 4; ++m) _Pragma("unroll") for (int k = 0; k < 2; ++k) dst[m][k] = *(const LAS bf16x8*)(lds + PG8_SA(b, h) + aoff + m * 2048 + k * 1024); } while (0)
; #define PG8_LDB(dst, b, h) do { _Pragma("unroll") for (int n = 0; n < 2; ++n) _Pragma("unroll") for (int k = 0; k < 2; ++k) dst[n][k] = *(const LAS bf16x8*)(lds + PG8_SB(b, h) + boff + n * 2048 + k * 1024); } while (0)
; #define PG8_MMA(ai, bj, At, Bt) do { __builtin_amdgcn_s_setprio(1); _Pragma("unroll") for (int m = 0; m < 4; ++m) _Pragma("unroll") for (int n = 0; n < 2; ++n) _Pragma("unroll") for (int k = 0; k < 2; ++k) \
;         acc[ai][bj][m][n] = __builtin_amdgcn_mfma_f32_16x16x32_bf16(Bt[n][k], At[m][k], acc[ai][bj][m][n], 0, 0, 0); __builtin_amdgcn_s_setprio(0); } while (0)
; #define PG8_WAIT_V(n) asm volatile("s_waitcnt vmcnt(" #n ")" ::: "memory")
; #define PG8_WAIT_L(n) asm volatile("s_waitcnt lgkmcnt(" #n ")" ::: "memory")
; #define PG8_BAR __builtin_amdgcn_s_barrier()
; #define PG8_SCHED __builtin_amdgcn_sched_barrier(0)
; template <class Epi>
; __device__ __forceinline__ void gemm_phase(LAS unsigned char* lds, const Gemm g, const StaticOrder& S, const Epi& E) {
;     ...
;             PG8_BAR; PG8_WAIT_L(0); PG8_MMA(0, 1, At, B1); PG8_BAR;
;             PG8_LDA(At, 0, 1); PG8_STAGE(PG8_SA(0, 0), a2, voffA);
;             PG8_BAR; PG8_WAIT_L(0); PG8_MMA(1, 0, At, B0); PG8_BAR; PG8_SCHED;
;             PG8_STAGE(PG8_SB(0, 1), b2 + hstepB, voffB);
;             PG8_WAIT_V(6); PG8_BAR; PG8_MMA(1, 1, At, B1); PG8_BAR;
;             PG8_LDB(B0, 1, 0); PG8_SCHED; PG8_LDA(At, 1, 0); PG8_STAGE(PG8_SA(0, 1), a2 + hstepA, voffA);
;             PG8_WAIT_L(8); PG8_BAR; PG8_WAIT_L(0); PG8_MMA(0, 0, At, B0); PG8_BAR; PG8_SCHED;
	s_waitcnt lgkmcnt(0)
	s_setprio 1
	s_waitcnt lgkmcnt(0)
	v_mfma_f32_16x16x32_bf16 v[96:99], v[72:75], v[120:123], v[96:99]
	v_mfma_f32_16x16x32_bf16 v[16:19], v[196:199], v[120:123], v[16:19]
	v_mfma_f32_16x16x32_bf16 v[20:23], v[72:75], v[152:155], v[20:23]
	v_mfma_f32_16x16x32_bf16 v[24:27], v[196:199], v[152:155], v[24:27]
	v_mfma_f32_16x16x32_bf16 v[28:31], v[72:75], v[160:163], v[28:31]
	v_mfma_f32_16x16x32_bf16 v[32:35], v[196:199], v[160:163], v[32:35]
	v_mfma_f32_16x16x32_bf16 v[36:39], v[72:75], v[180:183], v[36:39]
	v_mfma_f32_16x16x32_bf16 v[40:43], v[196:199], v[180:183], v[40:43]
	v_mfma_f32_16x16x32_bf16 v[96:99], v[192:195], v[124:127], v[96:99]
	v_mfma_f32_16x16x32_bf16 v[16:19], v[200:203], v[124:127], v[16:19]
	v_mfma_f32_16x16x32_bf16 v[20:23], v[192:195], v[156:159], v[20:23]
	v_mfma_f32_16x16x32_bf16 v[24:27], v[200:203], v[156:159], v[24:27]
	v_mfma_f32_16x16x32_bf16 v[28:31], v[192:195], v[164:167], v[28:31]
	v_mfma_f32_16x16x32_bf16 v[32:35], v[200:203], v[164:167], v[32:35]
	v_mfma_f32_16x16x32_bf16 v[36:39], v[192:195], v[184:187], v[36:39]
	v_mfma_f32_16x16x32_bf16 v[40:43], v[200:203], v[184:187], v[40:43]
	s_setprio 0
	s_mov_b32 m0, s8
	v_lshl_add_u64 v[248:249], s[48:49], 0, v[168:169]
	s_barrier
	ds_read_b128 v[120:123], v208 offset:16384
	ds_read_b128 v[124:127], v208 offset:17408
	ds_read_b128 v[152:155], v208 offset:18432
	ds_read_b128 v[156:159], v208 offset:19456
	ds_read_b128 v[160:163], v208 offset:20480
	ds_read_b128 v[164:167], v208 offset:21504
	ds_read_b128 v[180:183], v208 offset:22528
	ds_read_b128 v[184:187], v208 offset:23552
	global_load_lds_dwordx4 v[248:249], off
	v_lshl_add_u64 v[250:251], s[48:49], 0, v[172:173]
	s_mov_b32 m0, s9
	s_nop 0
	global_load_lds_dwordx4 v[250:251], off
	s_barrier
	s_waitcnt lgkmcnt(0)
	s_setprio 1
	s_waitcnt lgkmcnt(0)
	v_mfma_f32_16x16x32_bf16 v[136:139], v[104:107], v[152:155], v[136:139]
	v_mfma_f32_16x16x32_bf16 v[212:215], v[108:111], v[156:159], v[136:139]
	v_mfma_f32_16x16x32_bf16 v[136:139], v[112:115], v[152:155], v[140:143]
	v_mfma_f32_16x16x32_bf16 v[220:223], v[116:119], v[156:159], v[136:139]
	v_mfma_f32_16x16x32_bf16 v[136:139], v[104:107], v[160:163], v[144:147]
	v_mfma_f32_16x16x32_bf16 v[128:131], v[104:107], v[120:123], v[128:131]
	v_mfma_f32_16x16x32_bf16 v[132:135], v[112:115], v[120:123], v[132:135]
	v_mfma_f32_16x16x32_bf16 v[224:227], v[108:111], v[164:167], v[136:139]
	v_mfma_f32_16x16x32_bf16 v[136:139], v[112:115], v[160:163], v[148:151]
	v_mfma_f32_16x16x32_bf16 v[0:3], v[104:107], v[180:183], v[0:3]
	v_mfma_f32_16x16x32_bf16 v[4:7], v[112:115], v[180:183], v[4:7]
	v_mfma_f32_16x16x32_bf16 v[128:131], v[108:111], v[124:127], v[128:131]
	v_mfma_f32_16x16x32_bf16 v[132:135], v[116:119], v[124:127], v[132:135]
	v_mfma_f32_16x16x32_bf16 v[228:231], v[116:119], v[164:167], v[136:139]
	v_mfma_f32_16x16x32_bf16 v[0:3], v[108:111], v[184:187], v[0:3]
	v_mfma_f32_16x16x32_bf16 v[4:7], v[116:119], v[184:187], v[4:7]
	s_setprio 0
	s_barrier
	s_add_u32 s14, s46, 0x10000
	s_addc_u32 s15, s47, 0
	s_mov_b32 m0, s83
	v_lshl_add_u64 v[104:105], s[14:15], 0, v[170:171]
	global_load_lds_dwordx4 v[104:105], off
	v_lshl_add_u64 v[104:105], s[14:15], 0, v[174:175]
	s_mov_b32 m0, s81
	s_nop 0
	global_load_lds_dwordx4 v[104:105], off
	s_waitcnt vmcnt(6)
	s_barrier
	s_setprio 1
	v_mfma_f32_16x16x32_bf16 v[12:15], v[196:199], v[120:123], v[12:15]
	v_mfma_f32_16x16x32_bf16 v[104:107], v[200:203], v[124:127], v[12:15]
	v_mfma_f32_16x16x32_bf16 v[12:15], v[72:75], v[152:155], v[44:47]
	v_mfma_f32_16x16x32_bf16 v[44:47], v[192:195], v[156:159], v[12:15]
	v_mfma_f32_16x16x32_bf16 v[12:15], v[196:199], v[152:155], v[88:91]
	v_mfma_f32_16x16x32_bf16 v[108:111], v[200:203], v[156:159], v[12:15]
	v_mfma_f32_16x16x32_bf16 v[12:15], v[72:75], v[160:163], v[92:95]
	v_mfma_f32_16x16x32_bf16 v[92:95], v[192:195], v[164:167], v[12:15]
	v_mfma_f32_16x16x32_bf16 v[12:15], v[196:199], v[160:163], v[100:103]
	v_mfma_f32_16x16x32_bf16 v[100:103], v[200:203], v[164:167], v[12:15]
	v_mfma_f32_16x16x32_bf16 v[12:15], v[72:75], v[180:183], v[80:83]
	v_mfma_f32_16x16x32_bf16 v[8:11], v[72:75], v[120:123], v[8:11]
	v_mfma_f32_16x16x32_bf16 v[80:83], v[192:195], v[184:187], v[12:15]
	v_mfma_f32_16x16x32_bf16 v[12:15], v[196:199], v[180:183], v[84:87]
	v_mfma_f32_16x16x32_bf16 v[8:11], v[192:195], v[124:127], v[8:11]
	v_mfma_f32_16x16x32_bf16 v[180:183], v[200:203], v[184:187], v[12:15]
	s_setprio 0
	s_barrier
	ds_read_b128 v[116:119], v218
	ds_read_b128 v[124:127], v218 offset:1024
	ds_read_b128 v[184:187], v218 offset:2048
	ds_read_b128 v[192:195], v218 offset:3072
	s_add_u32 s14, s48, 0x40000
	s_addc_u32 s15, s49, 0
	s_mov_b32 m0, s35
	v_lshl_add_u64 v[72:73], s[14:15], 0, v[168:169]
	ds_read_b128 v[12:15], v208 offset:32768
	ds_read_b128 v[88:91], v208 offset:33792
	ds_read_b128 v[112:115], v208 offset:34816
	ds_read_b128 v[120:123], v208 offset:35840
	ds_read_b128 v[140:143], v208 offset:36864
	ds_read_b128 v[196:199], v208 offset:37888
	ds_read_b128 v[200:203], v208 offset:38912
	ds_read_b128 v[236:239], v208 offset:39936
	global_load_lds_dwordx4 v[72:73], off
	v_lshl_add_u64 v[72:73], s[14:15], 0, v[172:173]
	s_mov_b32 m0, s63
	s_nop 0
	global_load_lds_dwordx4 v[72:73], off
	s_waitcnt lgkmcnt(8)
	s_barrier
; #define PG8_STAGE(bufoff, gbase, voff) do { _Pragma("unroll") for (int _i = 0; _i < 2; ++_i) \
;         __builtin_amdgcn_global_load_lds((const unsigned*)((const char*)(gbase) + (voff)[_i]), (LAS unsigned*)(lds + (bufoff) + ldsw + _i * 8192), 16, 0, 0); } while (0)
; #define PG8_LDA(dst, b, h) do { _Pragma("unroll") for (int m = 0; m < 4; ++m) _Pragma("unroll") for (int k = 0; k < 2; ++k) dst[m][k] = *(const LAS bf16x8*)(lds + PG8_SA(b, h) + aoff + m * 2048 + k * 1024); } while (0)
; #define PG8_LDB(dst, b, h) do { _Pragma("unroll") for (int n = 0; n < 2; ++n) _Pragma("unroll") for (int k = 0; k < 2; ++k) dst[n][k] = *(const LAS bf16x8*)(lds + PG8_SB(b, h) + boff + n * 2048 + k * 1024); } while (0)
; #define PG8_MMA(ai, bj, At, Bt) do { __builtin_amdgcn_s_setprio(1); _Pragma("unroll") for (int m = 0; m < 4; ++m) _Pragma("unroll") for (int n = 0; n < 2; ++n) _Pragma("unroll") for (int k = 0; k < 2; ++k) \
;         acc[ai][bj][m][n] = __builtin_amdgcn_mfma_f32_16x16x32_bf16(Bt[n][k], At[m][k], acc[ai][bj][m][n], 0, 0, 0); __builtin_amdgcn_s_setprio(0); } while (0)
; template <class Epi>
; __device__ __forceinline__ void gemm_phase(LAS unsigned char* lds, const Gemm g, const StaticOrder& S, const Epi& E) {
;     ...
;             PG8_WAIT_L(8); PG8_BAR; PG8_WAIT_L(0); PG8_MMA(0, 0, At, B0); PG8_BAR; PG8_SCHED;
;             PG8_LDB(B1, 1, 1); PG8_STAGE(PG8_SB(1, 0), b3, voffB);
;             PG8_BAR; PG8_WAIT_L(0); PG8_MMA(0, 1, At, B1); PG8_BAR;
;             PG8_LDA(At, 1, 1); PG8_STAGE(PG8_SA(1, 0), a3, voffA);
;             PG8_BAR; PG8_WAIT_L(0); PG8_MMA(1, 0, At, B0); PG8_BAR; PG8_SCHED;
;             PG8_STAGE(PG8_SB(1, 1), b3 + hstepB, voffB);
;             PG8_WAIT_V(6); PG8_BAR; PG8_MMA(1, 1, At, B1); PG8_BAR;
;     __device__ __forceinline__ void operator()(AccRef acc, const Unit& u, int wr, int wc, int fr, int fq) const {
;         const int row0 = u.pm * 256 + wr * 64 + fr, col0 = u.pn * 128 + wc * 32 + 8 * fq;
;         u32x4 rws[2][4];
; #pragma unroll
;         for (int ai = 0; ai < 2; ++ai)
; #pragma unroll
;             for (int m = 0; m < 4; ++m) rws[ai][m] = *(const u32x4*)(REC + (size_t)(row0 + ai * 128 + m * 16) * D + col0);
; #pragma unroll
;         for (int n = 0; n < 2; ++n) {
;             const f32x4 ba = *(const f32x4*)(b_a + col0 + 4 * n), bx = *(const f32x4*)(b_x + col0 + 4 * n), l = *(const f32x4*)(lam + col0 + 4 * n);
	s_waitcnt lgkmcnt(0)
	s_setprio 1
	s_waitcnt lgkmcnt(0)
	v_mfma_f32_16x16x32_bf16 v[48:51], v[116:119], v[12:15], v[48:51]
	v_mfma_f32_16x16x32_bf16 v[160:163], v[124:127], v[88:91], v[48:51]
	v_mfma_f32_16x16x32_bf16 v[48:51], v[184:187], v[12:15], v[52:55]
	v_mfma_f32_16x16x32_bf16 v[84:87], v[192:195], v[88:91], v[48:51]
	v_mfma_f32_16x16x32_bf16 v[48:51], v[116:119], v[112:115], v[56:59]
	v_mfma_f32_16x16x32_bf16 v[152:155], v[124:127], v[120:123], v[48:51]
	v_mfma_f32_16x16x32_bf16 v[48:51], v[184:187], v[112:115], v[60:63]
	v_mfma_f32_16x16x32_bf16 v[72:75], v[192:195], v[120:123], v[48:51]
	v_mfma_f32_16x16x32_bf16 v[48:51], v[116:119], v[140:143], v[64:67]
	v_mfma_f32_16x16x32_bf16 v[144:147], v[124:127], v[196:199], v[48:51]
	v_mfma_f32_16x16x32_bf16 v[48:51], v[184:187], v[140:143], v[68:71]
	v_mfma_f32_16x16x32_bf16 v[60:63], v[192:195], v[196:199], v[48:51]
	v_mfma_f32_16x16x32_bf16 v[48:51], v[116:119], v[200:203], v[188:191]
	v_mfma_f32_16x16x32_bf16 v[136:139], v[124:127], v[236:239], v[48:51]
	v_mfma_f32_16x16x32_bf16 v[48:51], v[184:187], v[200:203], v[76:79]
	v_mfma_f32_16x16x32_bf16 v[48:51], v[192:195], v[236:239], v[48:51]
	s_setprio 0
	s_barrier
	s_mov_b32 m0, s86
	v_lshl_add_u64 v[52:53], v[216:217], 0, s[24:25]
	ds_read_b128 v[56:59], v235
	ds_read_b128 v[68:71], v235 offset:1024
	ds_read_b128 v[188:191], v235 offset:2048
	ds_read_b128 v[240:243], v235 offset:3072
	global_load_lds_dwordx4 v[52:53], off
	v_lshl_add_u64 v[52:53], v[232:233], 0, s[24:25]
	s_mov_b32 m0, s84
	s_nop 0
	global_load_lds_dwordx4 v[52:53], off
	s_barrier
	s_waitcnt lgkmcnt(0)
	s_setprio 1
	s_waitcnt lgkmcnt(0)
	v_mfma_f32_16x16x32_bf16 v[52:55], v[56:59], v[12:15], v[96:99]
	v_mfma_f32_16x16x32_bf16 v[12:15], v[188:191], v[12:15], v[16:19]
	v_mfma_f32_16x16x32_bf16 v[164:167], v[68:71], v[88:91], v[52:55]
	v_mfma_f32_16x16x32_bf16 v[88:91], v[240:243], v[88:91], v[12:15]
	v_mfma_f32_16x16x32_bf16 v[12:15], v[56:59], v[112:115], v[20:23]
	v_mfma_f32_16x16x32_bf16 v[156:159], v[68:71], v[120:123], v[12:15]
	v_mfma_f32_16x16x32_bf16 v[12:15], v[188:191], v[112:115], v[24:27]
	v_mfma_f32_16x16x32_bf16 v[76:79], v[240:243], v[120:123], v[12:15]
	v_mfma_f32_16x16x32_bf16 v[12:15], v[56:59], v[140:143], v[28:31]
	v_mfma_f32_16x16x32_bf16 v[148:151], v[68:71], v[196:199], v[12:15]
	v_mfma_f32_16x16x32_bf16 v[12:15], v[188:191], v[140:143], v[32:35]
	v_mfma_f32_16x16x32_bf16 v[64:67], v[240:243], v[196:199], v[12:15]
	v_mfma_f32_16x16x32_bf16 v[12:15], v[56:59], v[200:203], v[36:39]
	v_mfma_f32_16x16x32_bf16 v[140:143], v[68:71], v[236:239], v[12:15]
	v_mfma_f32_16x16x32_bf16 v[12:15], v[188:191], v[200:203], v[40:43]
	v_mfma_f32_16x16x32_bf16 v[52:55], v[240:243], v[236:239], v[12:15]
	s_setprio 0
	s_mov_b32 m0, s72
	s_nop 4
	v_lshl_add_u64 v[12:13], v[248:249], 0, s[24:25]
	s_barrier
	ds_read_b128 v[16:19], v208 offset:49152
	ds_read_b128 v[20:23], v208 offset:50176
	ds_read_b128 v[28:31], v208 offset:51200
	ds_read_b128 v[32:35], v208 offset:52224
	ds_read_b128 v[196:199], v208 offset:53248
	ds_read_b128 v[200:203], v208 offset:54272
	ds_read_b128 v[236:239], v208 offset:55296
	ds_read_b128 v[244:247], v208 offset:56320
	global_load_lds_dwordx4 v[12:13], off
	v_lshl_add_u64 v[12:13], v[250:251], 0, s[24:25]
	s_mov_b32 m0, s73
	s_nop 0
	global_load_lds_dwordx4 v[12:13], off
	s_barrier
	s_waitcnt lgkmcnt(0)
	s_setprio 1
	s_waitcnt lgkmcnt(0)
	v_mfma_f32_16x16x32_bf16 v[12:15], v[116:119], v[16:19], v[128:131]
	v_mfma_f32_16x16x32_bf16 v[128:131], v[124:127], v[20:23], v[12:15]
	v_mfma_f32_16x16x32_bf16 v[12:15], v[184:187], v[16:19], v[132:135]
	v_mfma_f32_16x16x32_bf16 v[36:39], v[192:195], v[20:23], v[12:15]
	v_mfma_f32_16x16x32_bf16 v[12:15], v[116:119], v[28:31], v[212:215]
	v_mfma_f32_16x16x32_bf16 v[120:123], v[124:127], v[32:35], v[12:15]
	v_mfma_f32_16x16x32_bf16 v[12:15], v[184:187], v[28:31], v[220:223]
	v_mfma_f32_16x16x32_bf16 v[24:27], v[192:195], v[32:35], v[12:15]
	v_mfma_f32_16x16x32_bf16 v[12:15], v[116:119], v[196:199], v[224:227]
	v_mfma_f32_16x16x32_bf16 v[0:3], v[116:119], v[236:239], v[0:3]
	v_mfma_f32_16x16x32_bf16 v[112:115], v[124:127], v[200:203], v[12:15]
	v_mfma_f32_16x16x32_bf16 v[12:15], v[184:187], v[196:199], v[228:231]
	v_mfma_f32_16x16x32_bf16 v[96:99], v[124:127], v[244:247], v[0:3]
	v_mfma_f32_16x16x32_bf16 v[0:3], v[184:187], v[236:239], v[4:7]
	v_mfma_f32_16x16x32_bf16 v[12:15], v[192:195], v[200:203], v[12:15]
	v_mfma_f32_16x16x32_bf16 v[0:3], v[192:195], v[244:247], v[0:3]
	s_setprio 0
	s_barrier
	s_add_u32 s14, s46, 0x10080
	s_addc_u32 s15, s47, 0
	s_mov_b32 m0, s17
	v_lshl_add_u64 v[4:5], s[14:15], 0, v[170:171]
	global_load_lds_dwordx4 v[4:5], off
	v_lshl_add_u64 v[4:5], s[14:15], 0, v[174:175]
	s_mov_b32 m0, s16
	s_nop 0
	global_load_lds_dwordx4 v[4:5], off
	s_waitcnt vmcnt(6)
	s_barrier
	s_setprio 1
	v_mfma_f32_16x16x32_bf16 v[4:7], v[56:59], v[16:19], v[8:11]
	v_mfma_f32_16x16x32_bf16 v[132:135], v[68:71], v[20:23], v[4:7]
	v_mfma_f32_16x16x32_bf16 v[4:7], v[188:191], v[16:19], v[104:107]
	v_mfma_f32_16x16x32_bf16 v[40:43], v[240:243], v[20:23], v[4:7]
	v_mfma_f32_16x16x32_bf16 v[4:7], v[56:59], v[28:31], v[44:47]
	v_mfma_f32_16x16x32_bf16 v[124:127], v[68:71], v[32:35], v[4:7]
	v_mfma_f32_16x16x32_bf16 v[4:7], v[188:191], v[28:31], v[108:111]
	v_mfma_f32_16x16x32_bf16 v[28:31], v[240:243], v[32:35], v[4:7]
	v_mfma_f32_16x16x32_bf16 v[4:7], v[56:59], v[196:199], v[92:95]
	v_mfma_f32_16x16x32_bf16 v[116:119], v[68:71], v[200:203], v[4:7]
	v_mfma_f32_16x16x32_bf16 v[4:7], v[188:191], v[196:199], v[100:103]
	v_mfma_f32_16x16x32_bf16 v[16:19], v[240:243], v[200:203], v[4:7]
	v_mfma_f32_16x16x32_bf16 v[4:7], v[56:59], v[236:239], v[80:83]
	v_mfma_f32_16x16x32_bf16 v[100:103], v[68:71], v[244:247], v[4:7]
	v_mfma_f32_16x16x32_bf16 v[4:7], v[188:191], v[236:239], v[180:183]
	v_mfma_f32_16x16x32_bf16 v[4:7], v[240:243], v[244:247], v[4:7]
	s_setprio 0
	s_nop 0
	v_lshl_or_b32 v180, s13, 7, v206
	v_ashrrev_i32_e32 v181, 31, v180
	v_lshlrev_b64 v[8:9], 2, v[180:181]
	v_lshl_add_u64 v[184:185], s[22:23], 0, v[8:9]
	s_barrier
; __device__ __forceinline__ float bflo(unsigned w) { return __uint_as_float(w << 16); }
; __device__ __forceinline__ float bfhi(unsigned w) { return __uint_as_float(w & 0xffff0000u); }
; __device__ __forceinline__ float sigmoidf_(float x) { return __builtin_amdgcn_rcpf(1.0f + __expf(-x)); }
;     __device__ __forceinline__ void operator()(AccRef acc, const Unit& u, int wr, int wc, int fr, int fq) const {
;         const int row0 = u.pm * 256 + wr * 64 + fr, col0 = u.pn * 128 + wc * 32 + 8 * fq;
;         u32x4 rws[2][4];
; #pragma unroll
;         for (int ai = 0; ai < 2; ++ai)
; #pragma unroll
;             for (int m = 0; m < 4; ++m) rws[ai][m] = *(const u32x4*)(REC + (size_t)(row0 + ai * 128 + m * 16) * D + col0);
; #pragma unroll
;         for (int n = 0; n < 2; ++n) {
;             const f32x4 ba = *(const f32x4*)(b_a + col0 + 4 * n), bx = *(const f32x4*)(b_x + col0 + 4 * n), l = *(const f32x4*)(lam + col0 + 4 * n);
;             f32x4 k8;
; #pragma unroll
;             for (int j = 0; j < 4; ++j) k8[j] = -8.0f * __logf(1.0f + __expf(-l[j]));
; #pragma unroll
;             for (int ai = 0; ai < 2; ++ai)
; #pragma unroll
;                 for (int m = 0; m < 4; ++m) { const size_t off = (size_t)(row0 + ai * 128 + m * 16) * D + col0 + 4 * n;
;                     float lo[4], bo[4];
; #pragma unroll
;                     for (int j = 0; j < 4; ++j) { const unsigned w = rws[ai][m][2 * n + (j >> 1)]; const float rec = (j & 1) ? bfhi(w) : bflo(w);
;                         const float r = sigmoidf_(acc[ai][0][m][n][j] + ba[j]), ig = sigmoidf_(acc[ai][1][m][n][j] + bx[j]);
;                         const float la = k8[j] * r; const float mult = __builtin_sqrtf(1.0f - __expf(2.0f * la));
	global_load_dwordx4 v[212:215], v[184:185], off
	v_lshl_add_u64 v[186:187], s[26:27], 0, v[8:9]
	global_load_dwordx4 v[108:111], v[186:187], off
	v_lshl_add_u64 v[188:189], s[20:21], 0, v[8:9]
	global_load_dwordx4 v[104:107], v[188:189], off
	v_lshl_add_u32 v182, s12, 8, v204
	v_or_b32_e32 v202, 16, v182
	v_or_b32_e32 v200, 32, v182
	v_or_b32_e32 v198, 48, v182
	v_add_u32_e32 v196, 0x80, v182
	v_add_u32_e32 v194, 0x90, v182
	v_add_u32_e32 v192, 0xa0, v182
	v_add_u32_e32 v190, 0xb0, v182
	v_ashrrev_i32_e32 v183, 31, v182
	v_ashrrev_i32_e32 v203, 31, v202
	v_ashrrev_i32_e32 v201, 31, v200
	v_ashrrev_i32_e32 v199, 31, v198
	v_ashrrev_i32_e32 v197, 31, v196
	v_ashrrev_i32_e32 v195, 31, v194
	v_ashrrev_i32_e32 v193, 31, v192
	v_ashrrev_i32_e32 v191, 31, v190
	v_lshl_add_u64 v[10:11], v[180:181], 1, s[18:19]
	v_lshlrev_b64 v[20:21], 11, v[182:183]
	v_lshlrev_b64 v[22:23], 11, v[202:203]
	v_lshlrev_b64 v[32:33], 11, v[200:201]
	v_lshlrev_b64 v[34:35], 11, v[198:199]
	v_lshlrev_b64 v[44:45], 11, v[196:197]
	v_lshlrev_b64 v[46:47], 11, v[194:195]
	v_lshlrev_b64 v[56:57], 11, v[192:193]
	v_lshlrev_b64 v[58:59], 11, v[190:191]
	v_lshl_add_u64 v[20:21], v[10:11], 0, v[20:21]
	v_lshl_add_u64 v[8:9], v[10:11], 0, v[22:23]
	v_lshl_add_u64 v[22:23], v[10:11], 0, v[32:33]
	v_lshl_add_u64 v[32:33], v[10:11], 0, v[34:35]
	v_lshl_add_u64 v[34:35], v[10:11], 0, v[44:45]
	v_lshl_add_u64 v[216:217], v[10:11], 0, v[46:47]
	v_lshl_add_u64 v[220:221], v[10:11], 0, v[56:57]
	v_lshl_add_u64 v[10:11], v[10:11], 0, v[58:59]
	global_load_dwordx4 v[92:95], v[20:21], off
	global_load_dwordx4 v[80:83], v[8:9], off
	global_load_dwordx4 v[68:71], v[22:23], off
	global_load_dwordx4 v[56:59], v[32:33], off
	global_load_dwordx4 v[44:47], v[34:35], off
	s_nop 0
	global_load_dwordx4 v[32:35], v[216:217], off
	global_load_dwordx4 v[20:23], v[220:221], off
	s_nop 0
	global_load_dwordx4 v[8:11], v[10:11], off
	v_lshlrev_b64 v[182:183], 10, v[182:183]
	s_add_i32 s74, s74, s50
	s_waitcnt vmcnt(0)
	v_mul_f32_e32 v212, 0xbfb8aa3b, v212
	v_exp_f32_e32 v212, v212
	v_mul_f32_e32 v213, 0xbfb8aa3b, v213
	v_mul_f32_e32 v214, 0xbfb8aa3b, v214
	v_exp_f32_e32 v213, v213
	v_mul_f32_e32 v215, 0xbfb8aa3b, v215
	v_exp_f32_e32 v214, v214
	v_add_f32_e32 v212, 1.0, v212
	v_exp_f32_e32 v215, v215
	v_cmp_gt_f32_e32 vcc, s77, v212
	v_add_f32_e32 v213, 1.0, v213
	v_add_f32_e32 v214, 1.0, v214
	v_cndmask_b32_e64 v216, 0, 32, vcc
	v_ldexp_f32 v212, v212, v216
	v_cmp_gt_f32_e64 s[12:13], s77, v213
	v_log_f32_e32 v212, v212
	v_add_f32_e32 v215, 1.0, v215
	v_cndmask_b32_e64 v217, 0, 32, s[12:13]
	v_cmp_gt_f32_e64 s[14:15], s77, v214
	v_cmp_gt_f32_e64 s[16:17], s77, v215
	v_ldexp_f32 v213, v213, v217
	v_cndmask_b32_e64 v218, 0, 32, s[14:15]
	v_cndmask_b32_e64 v220, 0, 32, s[16:17]
	v_ldexp_f32 v214, v214, v218
	v_log_f32_e32 v213, v213
	v_ldexp_f32 v215, v215, v220
	v_log_f32_e32 v214, v214
	v_mul_f32_e32 v220, 0x3f317217, v212
	v_log_f32_e32 v215, v215
	v_fma_f32 v220, v212, s78, -v220
	v_fmac_f32_e32 v220, 0x3377d1cf, v212
	v_add_f32_e32 v160, v160, v108
	v_add_f32_e32 v161, v161, v109
	v_cndmask_b32_e32 v216, 0, v210, vcc
	v_mul_f32_e32 v221, 0x3f317217, v213
	v_fmac_f32_e32 v220, 0x3f317217, v212
	v_cmp_lt_f32_e64 vcc, |v212|, s79
	v_mul_f32_e32 v160, 0xbfb8aa3b, v160
	v_mul_f32_e32 v161, 0xbfb8aa3b, v161
	v_add_f32_e32 v162, v162, v110
	v_mul_f32_e32 v222, 0x3f317217, v214
	v_fma_f32 v221, v213, s78, -v221
	v_cndmask_b32_e32 v212, v212, v220, vcc
	v_exp_f32_e32 v160, v160
	v_exp_f32_e32 v161, v161
	v_mul_f32_e32 v162, 0xbfb8aa3b, v162
	v_add_f32_e32 v166, v166, v106
	v_fma_f32 v222, v214, s78, -v222
	v_fmac_f32_e32 v221, 0x3377d1cf, v213
	v_sub_f32_e32 v212, v212, v216
	v_mul_f32_e32 v216, 0x3f317217, v215
	v_exp_f32_e32 v162, v162
	v_mul_f32_e32 v166, 0xbfb8aa3b, v166
	v_add_f32_e32 v163, v163, v111
	v_fmac_f32_e32 v222, 0x3377d1cf, v214
	v_fmac_f32_e32 v221, 0x3f317217, v213
	v_cmp_lt_f32_e64 vcc, |v213|, s79
	v_fma_f32 v216, v215, s78, -v216
	v_exp_f32_e32 v166, v166
	v_mul_f32_e32 v163, 0xbfb8aa3b, v163
	v_fmac_f32_e32 v222, 0x3f317217, v214
	v_cndmask_b32_e32 v213, v213, v221, vcc
	v_cmp_lt_f32_e64 vcc, |v214|, s79
	v_fmac_f32_e32 v216, 0x3377d1cf, v215
	v_exp_f32_e32 v163, v163
	v_cndmask_b32_e32 v214, v214, v222, vcc
	v_fmac_f32_e32 v216, 0x3f317217, v215
	v_cmp_lt_f32_e64 vcc, |v215|, s79
	v_add_f32_e32 v160, 1.0, v160
	v_add_f32_e32 v161, 1.0, v161
	v_cndmask_b32_e32 v215, v215, v216, vcc
	v_cndmask_b32_e64 v216, 0, v210, s[16:17]
	v_rcp_f32_e32 v160, v160
	v_rcp_f32_e32 v161, v161
	v_add_f32_e32 v162, 1.0, v162
	v_cndmask_b32_e64 v217, 0, v210, s[12:13]
	v_sub_f32_e32 v215, v215, v216
	v_rcp_f32_e32 v216, v162
	v_add_f32_e32 v162, 1.0, v166
	v_sub_f32_e32 v213, v213, v217
	v_rcp_f32_e32 v166, v162
	v_add_f32_e32 v162, 1.0, v163
	v_rcp_f32_e32 v217, v162
	v_pk_mul_f32 v[162:163], v[212:213], s[34:35] op_sel_hi:[1,0]
	v_cndmask_b32_e64 v218, 0, v210, s[14:15]
	v_pk_mul_f32 v[212:213], v[160:161], v[162:163]
	v_add_f32_e32 v161, v167, v107
	v_add_f32_e32 v160, v212, v212
	v_mul_f32_e32 v160, 0x3fb8aa3b, v160
	v_exp_f32_e32 v160, v160
	v_mul_f32_e32 v161, 0xbfb8aa3b, v161
	v_exp_f32_e32 v161, v161
	v_sub_f32_e32 v214, v214, v218
	v_sub_f32_e32 v160, 1.0, v160
	v_add_f32_e32 v161, 1.0, v161
	v_add_f32_e32 v223, v213, v213
	v_sqrt_f32_e32 v218, v160
	v_rcp_f32_e32 v167, v161
	v_mul_f32_e32 v223, 0x3fb8aa3b, v223
	v_exp_f32_e32 v223, v223
	v_add_u32_e32 v161, -1, v218
	v_fma_f32 v222, -v161, v218, v160
	v_cmp_ge_f32_e64 s[12:13], 0, v222
	v_add_u32_e32 v222, 1, v218
	v_cvt_pk_bf16_f32 v212, v212, v213
	v_cndmask_b32_e64 v161, v218, v161, s[12:13]
	v_fma_f32 v218, -v222, v218, v160
; __device__ __forceinline__ float bflo(unsigned w) { return __uint_as_float(w << 16); }
; __device__ __forceinline__ float bfhi(unsigned w) { return __uint_as_float(w & 0xffff0000u); }
; __device__ __forceinline__ float sigmoidf_(float x) { return __builtin_amdgcn_rcpf(1.0f + __expf(-x)); }
;     __device__ __forceinline__ void operator()(AccRef acc, const Unit& u, int wr, int wc, int fr, int fq) const {
;     ...
;             for (int ai = 0; ai < 2; ++ai)
; #pragma unroll
;                 for (int m = 0; m < 4; ++m) { const size_t off = (size_t)(row0 + ai * 128 + m * 16) * D + col0 + 4 * n;
;                     float lo[4], bo[4];
; #pragma unroll
;                     for (int j = 0; j < 4; ++j) { const unsigned w = rws[ai][m][2 * n + (j >> 1)]; const float rec = (j & 1) ? bfhi(w) : bflo(w);
;                         const float r = sigmoidf_(acc[ai][0][m][n][j] + ba[j]), ig = sigmoidf_(acc[ai][1][m][n][j] + bx[j]);
;                         const float la = k8[j] * r; const float mult = __builtin_sqrtf(1.0f - __expf(2.0f * la));
;                         lo[j] = la; bo[j] = mult * ig * rec; }
;                     *(u32x2*)(LA + off) = (u32x2){cvt_pk_bf16(lo[0], lo[1]), cvt_pk_bf16(lo[2], lo[3])}; *(u32x2*)(BV + off) = (u32x2){cvt_pk_bf16(bo[0], bo[1]), cvt_pk_bf16(bo[2], bo[3])}; }
	v_cmp_lt_f32_e64 s[12:13], 0, v218
	v_add_f32_e32 v164, v164, v104
	v_add_f32_e32 v165, v165, v105
	v_cndmask_b32_e64 v161, v161, v222, s[12:13]
	v_sub_f32_e32 v222, 1.0, v223
	v_mov_b32_e32 v223, v222
	v_sqrt_f32_e32 v224, v223
	v_mul_f32_e32 v164, 0xbfb8aa3b, v164
	v_mul_f32_e32 v165, 0xbfb8aa3b, v165
	v_mov_b32_e32 v222, v161
	v_add_u32_e32 v160, -1, v224
	v_fma_f32 v161, -v160, v224, v223
	v_cmp_ge_f32_e32 vcc, 0, v161
	v_add_u32_e32 v225, 1, v224
	v_exp_f32_e32 v164, v164
	v_cndmask_b32_e32 v218, v224, v160, vcc
	v_pk_mul_f32 v[160:161], v[214:215], s[34:35] op_sel_hi:[1,0]
	v_fma_f32 v224, -v225, v224, v223
	v_pk_mul_f32 v[214:215], v[216:217], v[160:161]
	v_cmp_lt_f32_e32 vcc, 0, v224
	v_add_f32_e32 v216, v214, v214
	v_mul_f32_e32 v216, 0x3fb8aa3b, v216
	v_exp_f32_e32 v216, v216
	v_cndmask_b32_e32 v217, v218, v225, vcc
	v_sub_f32_e32 v216, 1.0, v216
	v_add_f32_e32 v224, v215, v215
	v_mul_f32_e32 v224, 0x3fb8aa3b, v224
	v_sqrt_f32_e32 v218, v216
	v_exp_f32_e32 v224, v224
	v_exp_f32_e32 v165, v165
	v_add_u32_e32 v213, -1, v218
	v_mov_b32_e32 v223, v217
	v_fma_f32 v217, -v213, v218, v216
	v_cmp_ge_f32_e64 s[12:13], 0, v217
	v_add_u32_e32 v217, 1, v218
	v_add_f32_e32 v164, 1.0, v164
	v_cndmask_b32_e64 v213, v218, v213, s[12:13]
	v_fma_f32 v218, -v217, v218, v216
	v_cmp_lt_f32_e64 s[12:13], 0, v218
	v_sub_f32_e32 v218, 1.0, v224
	s_nop 0
	v_cndmask_b32_e64 v213, v213, v217, s[12:13]
	v_sqrt_f32_e32 v224, v218
	v_add_f32_e32 v165, 1.0, v165
	v_rcp_f32_e32 v164, v164
	v_mov_b32_e32 v216, v213
	v_add_u32_e32 v213, -1, v224
	v_fma_f32 v217, -v213, v224, v218
	v_cmp_ge_f32_e32 vcc, 0, v217
	v_add_u32_e32 v217, 1, v224
	v_rcp_f32_e32 v165, v165
	v_cndmask_b32_e32 v213, v224, v213, vcc
	v_fma_f32 v224, -v217, v224, v218
	v_cmp_lt_f32_e32 vcc, 0, v224
	v_add_f32_e32 v152, v152, v108
	v_lshl_add_u64 v[220:221], v[182:183], 0, v[180:181]
	v_cndmask_b32_e32 v213, v213, v217, vcc
	v_mul_f32_e32 v152, 0xbfb8aa3b, v152
	v_exp_f32_e32 v152, v152
	v_mov_b32_e32 v217, v213
	v_cvt_pk_bf16_f32 v213, v214, v215
	v_lshlrev_b64 v[214:215], 1, v[220:221]
	v_lshl_add_u64 v[220:221], s[70:71], 0, v[214:215]
	global_store_dwordx2 v[220:221], v[212:213], off
	v_lshlrev_b32_e32 v212, 16, v92
	v_and_b32_e32 v213, 0xffff0000, v92
	v_pk_mul_f32 v[164:165], v[164:165], v[222:223]
	v_pk_mul_f32 v[166:167], v[166:167], v[216:217]
	v_pk_mul_f32 v[164:165], v[164:165], v[212:213]
	v_add_f32_e32 v153, v153, v109
	v_cvt_pk_bf16_f32 v92, v164, v165
	v_lshlrev_b32_e32 v164, 16, v93
	v_and_b32_e32 v165, 0xffff0000, v93
	v_add_f32_e32 v93, 1.0, v152
	v_rcp_f32_e32 v152, v93
	v_pk_mul_f32 v[164:165], v[166:167], v[164:165]
	v_mul_f32_e32 v153, 0xbfb8aa3b, v153
	v_cvt_pk_bf16_f32 v93, v164, v165
	v_lshl_add_u64 v[164:165], s[68:69], 0, v[214:215]
	v_mul_f32_e32 v166, v152, v162
	global_store_dwordx2 v[164:165], v[92:93], off
	v_add_f32_e32 v92, v166, v166
	v_mul_f32_e32 v92, 0x3fb8aa3b, v92
	v_exp_f32_e32 v92, v92
	v_add_f32_e32 v93, v156, v104
	v_mul_f32_e32 v93, 0xbfb8aa3b, v93
	v_exp_f32_e32 v152, v93
	v_sub_f32_e32 v92, 1.0, v92
	v_exp_f32_e32 v153, v153
	v_add_f32_e32 v154, v154, v110
	v_mov_b32_e32 v156, v92
	v_sqrt_f32_e32 v164, v156
	v_add_f32_e32 v153, 1.0, v153
	v_rcp_f32_e32 v153, v153
	v_add_f32_e32 v157, v157, v105
	v_add_u32_e32 v165, -1, v164
	v_fma_f32 v167, -v165, v164, v156
	v_cmp_ge_f32_e64 s[12:13], 0, v167
	v_add_u32_e32 v167, 1, v164
	v_mul_f32_e32 v154, 0xbfb8aa3b, v154
	v_cndmask_b32_e64 v165, v164, v165, s[12:13]
	v_fma_f32 v164, -v167, v164, v156
	v_cmp_lt_f32_e64 s[12:13], 0, v164
	v_mul_f32_e32 v157, 0xbfb8aa3b, v157
	v_exp_f32_e32 v154, v154
	v_cndmask_b32_e64 v164, v165, v167, s[12:13]
	v_mul_f32_e32 v167, v153, v163
	v_add_f32_e32 v153, v167, v167
	v_mul_f32_e32 v153, 0x3fb8aa3b, v153
	v_exp_f32_e32 v153, v153
	v_lshlrev_b64 v[92:93], 10, v[202:203]
	v_sub_f32_e32 v153, 1.0, v153
	v_exp_f32_e32 v157, v157
	v_add_f32_e32 v154, 1.0, v154
	v_mov_b32_e32 v165, v153
	v_sqrt_f32_e32 v202, v165
	v_add_f32_e32 v153, 1.0, v157
	v_rcp_f32_e32 v154, v154
	v_add_u32_e32 v157, -1, v202
	v_mov_b32_e32 v156, v164
	v_fma_f32 v164, -v157, v202, v165
	v_cmp_ge_f32_e64 s[12:13], 0, v164
	v_add_u32_e32 v164, 1, v202
	v_add_f32_e32 v155, v155, v111
	v_cndmask_b32_e64 v157, v202, v157, s[12:13]
	v_fma_f32 v202, -v164, v202, v165
	v_cmp_lt_f32_e64 s[12:13], 0, v202
	v_mul_f32_e32 v202, v154, v160
	v_add_f32_e32 v154, v202, v202
	v_mul_f32_e32 v154, 0x3fb8aa3b, v154
	v_exp_f32_e32 v154, v154
	v_cndmask_b32_e64 v157, v157, v164, s[12:13]
	v_sub_f32_e32 v154, 1.0, v154
	v_add_f32_e32 v158, v158, v106
	v_mul_f32_e32 v155, 0xbfb8aa3b, v155
	v_mul_f32_e32 v158, 0xbfb8aa3b, v158
	v_mov_b32_e32 v164, v154
	v_exp_f32_e32 v155, v155
	v_exp_f32_e32 v158, v158
	v_sqrt_f32_e32 v203, v164
	v_add_f32_e32 v155, 1.0, v155
	v_add_f32_e32 v154, 1.0, v158
	v_add_u32_e32 v158, -1, v203
	v_rcp_f32_e32 v155, v155
	v_fma_f32 v165, -v158, v203, v164
	v_cmp_ge_f32_e64 s[12:13], 0, v165
	v_add_u32_e32 v165, 1, v203
	v_add_f32_e32 v159, v159, v107
	v_cndmask_b32_e64 v158, v203, v158, s[12:13]
	v_fma_f32 v203, -v165, v203, v164
	v_cmp_lt_f32_e64 s[12:13], 0, v203
	v_mul_f32_e32 v203, v155, v161
	v_add_f32_e32 v155, v203, v203
	v_mul_f32_e32 v155, 0x3fb8aa3b, v155
	v_exp_f32_e32 v155, v155
	v_cndmask_b32_e64 v158, v158, v165, s[12:13]
	v_sub_f32_e32 v155, 1.0, v155
	v_mul_f32_e32 v159, 0xbfb8aa3b, v159
	v_exp_f32_e32 v159, v159
	v_mov_b32_e32 v165, v155
	v_sqrt_f32_e32 v212, v165
	v_add_f32_e32 v155, 1.0, v159
	v_add_f32_e32 v152, 1.0, v152
	v_add_u32_e32 v159, -1, v212
	v_fma_f32 v164, -v159, v212, v165
	v_cmp_ge_f32_e64 s[12:13], 0, v164
	v_add_u32_e32 v164, 1, v212
	v_rcp_f32_e32 v152, v152
; __device__ __forceinline__ float bflo(unsigned w) { return __uint_as_float(w << 16); }
; __device__ __forceinline__ float bfhi(unsigned w) { return __uint_as_float(w & 0xffff0000u); }
; __device__ __forceinline__ float sigmoidf_(float x) { return __builtin_amdgcn_rcpf(1.0f + __expf(-x)); }
;     __device__ __forceinline__ void operator()(AccRef acc, const Unit& u, int wr, int wc, int fr, int fq) const {
;     ...
;             for (int ai = 0; ai < 2; ++ai)
; #pragma unroll
;                 for (int m = 0; m < 4; ++m) { const size_t off = (size_t)(row0 + ai * 128 + m * 16) * D + col0 + 4 * n;
;                     float lo[4], bo[4];
; #pragma unroll
;                     for (int j = 0; j < 4; ++j) { const unsigned w = rws[ai][m][2 * n + (j >> 1)]; const float rec = (j & 1) ? bfhi(w) : bflo(w);
;                         const float r = sigmoidf_(acc[ai][0][m][n][j] + ba[j]), ig = sigmoidf_(acc[ai][1][m][n][j] + bx[j]);
;                         const float la = k8[j] * r; const float mult = __builtin_sqrtf(1.0f - __expf(2.0f * la));
;                         lo[j] = la; bo[j] = mult * ig * rec; }
;                     *(u32x2*)(LA + off) = (u32x2){cvt_pk_bf16(lo[0], lo[1]), cvt_pk_bf16(lo[2], lo[3])}; *(u32x2*)(BV + off) = (u32x2){cvt_pk_bf16(bo[0], bo[1]), cvt_pk_bf16(bo[2], bo[3])}; }
	v_cndmask_b32_e64 v159, v212, v159, s[12:13]
	v_fma_f32 v212, -v164, v212, v165
	v_cmp_lt_f32_e64 s[12:13], 0, v212
	v_rcp_f32_e32 v153, v153
	v_add_f32_e32 v144, v144, v108
	v_cndmask_b32_e64 v159, v159, v164, s[12:13]
	v_mul_f32_e32 v144, 0xbfb8aa3b, v144
	v_exp_f32_e32 v144, v144
	v_lshl_add_u64 v[164:165], v[92:93], 0, v[180:181]
	v_lshlrev_b64 v[164:165], 1, v[164:165]
	v_cvt_pk_bf16_f32 v166, v166, v167
	v_cvt_pk_bf16_f32 v167, v202, v203
	v_lshl_add_u64 v[202:203], s[70:71], 0, v[164:165]
	global_store_dwordx2 v[202:203], v[166:167], off
	v_lshlrev_b32_e32 v166, 16, v80
	v_and_b32_e32 v167, 0xffff0000, v80
	v_pk_mul_f32 v[152:153], v[152:153], v[156:157]
	v_rcp_f32_e32 v154, v154
	v_rcp_f32_e32 v155, v155
	v_pk_mul_f32 v[152:153], v[152:153], v[166:167]
	v_add_f32_e32 v145, v145, v109
	v_cvt_pk_bf16_f32 v80, v152, v153
	v_lshlrev_b32_e32 v152, 16, v81
	v_and_b32_e32 v153, 0xffff0000, v81
	v_add_f32_e32 v81, 1.0, v144
	v_rcp_f32_e32 v144, v81
	v_pk_mul_f32 v[154:155], v[154:155], v[158:159]
	v_mul_f32_e32 v145, 0xbfb8aa3b, v145
	v_pk_mul_f32 v[152:153], v[154:155], v[152:153]
	v_mul_f32_e32 v154, v144, v162
	v_cvt_pk_bf16_f32 v81, v152, v153
	v_lshl_add_u64 v[152:153], s[68:69], 0, v[164:165]
	global_store_dwordx2 v[152:153], v[80:81], off
	v_add_f32_e32 v80, v154, v154
	v_mul_f32_e32 v80, 0x3fb8aa3b, v80
	v_exp_f32_e32 v80, v80
	v_add_f32_e32 v81, v148, v104
	v_mul_f32_e32 v81, 0xbfb8aa3b, v81
	v_exp_f32_e32 v144, v81
	v_sub_f32_e32 v80, 1.0, v80
	v_exp_f32_e32 v145, v145
	v_add_f32_e32 v146, v146, v110
	v_mov_b32_e32 v148, v80
	v_sqrt_f32_e32 v152, v148
	v_add_f32_e32 v145, 1.0, v145
	v_rcp_f32_e32 v145, v145
	v_add_f32_e32 v149, v149, v105
	v_add_u32_e32 v153, -1, v152
	v_fma_f32 v155, -v153, v152, v148
	v_cmp_ge_f32_e64 s[12:13], 0, v155
	v_add_u32_e32 v155, 1, v152
	v_mul_f32_e32 v146, 0xbfb8aa3b, v146
	v_cndmask_b32_e64 v153, v152, v153, s[12:13]
	v_fma_f32 v152, -v155, v152, v148
	v_cmp_lt_f32_e64 s[12:13], 0, v152
	v_mul_f32_e32 v149, 0xbfb8aa3b, v149
	v_exp_f32_e32 v146, v146
	v_cndmask_b32_e64 v152, v153, v155, s[12:13]
	v_mul_f32_e32 v155, v145, v163
	v_add_f32_e32 v145, v155, v155
	v_mul_f32_e32 v145, 0x3fb8aa3b, v145
	v_exp_f32_e32 v145, v145
	v_exp_f32_e32 v149, v149
	v_sub_f32_e32 v145, 1.0, v145
	v_add_f32_e32 v146, 1.0, v146
	v_mov_b32_e32 v153, v145
	v_sqrt_f32_e32 v156, v153
	v_add_f32_e32 v145, 1.0, v149
	v_rcp_f32_e32 v146, v146
	v_mov_b32_e32 v148, v152
	v_add_u32_e32 v149, -1, v156
	v_fma_f32 v152, -v149, v156, v153
	v_cmp_ge_f32_e64 s[12:13], 0, v152
	v_add_u32_e32 v152, 1, v156
	v_add_f32_e32 v147, v147, v111
	v_cndmask_b32_e64 v149, v156, v149, s[12:13]
	v_fma_f32 v156, -v152, v156, v153
	v_cmp_lt_f32_e64 s[12:13], 0, v156
	v_mul_f32_e32 v156, v146, v160
	v_add_f32_e32 v146, v156, v156
	v_mul_f32_e32 v146, 0x3fb8aa3b, v146
	v_exp_f32_e32 v146, v146
	v_cndmask_b32_e64 v149, v149, v152, s[12:13]
	v_sub_f32_e32 v146, 1.0, v146
	v_add_f32_e32 v150, v150, v106
	v_mul_f32_e32 v147, 0xbfb8aa3b, v147
	v_mul_f32_e32 v150, 0xbfb8aa3b, v150
	v_mov_b32_e32 v152, v146
	v_exp_f32_e32 v147, v147
	v_exp_f32_e32 v150, v150
	v_sqrt_f32_e32 v157, v152
	v_add_f32_e32 v147, 1.0, v147
	v_add_f32_e32 v146, 1.0, v150
	v_add_u32_e32 v150, -1, v157
	v_rcp_f32_e32 v147, v147
	v_fma_f32 v153, -v150, v157, v152
	v_cmp_ge_f32_e64 s[12:13], 0, v153
	v_add_u32_e32 v153, 1, v157
	v_add_f32_e32 v151, v151, v107
	v_cndmask_b32_e64 v150, v157, v150, s[12:13]
	v_fma_f32 v157, -v153, v157, v152
	v_cmp_lt_f32_e64 s[12:13], 0, v157
	v_mul_f32_e32 v157, v147, v161
	v_add_f32_e32 v147, v157, v157
	v_mul_f32_e32 v147, 0x3fb8aa3b, v147
	v_exp_f32_e32 v147, v147
	v_cndmask_b32_e64 v150, v150, v153, s[12:13]
	v_sub_f32_e32 v147, 1.0, v147
	v_mul_f32_e32 v151, 0xbfb8aa3b, v151
	v_exp_f32_e32 v151, v151
	v_mov_b32_e32 v153, v147
	v_sqrt_f32_e32 v158, v153
	v_add_f32_e32 v147, 1.0, v151
	v_add_f32_e32 v144, 1.0, v144
	v_add_u32_e32 v151, -1, v158
	v_fma_f32 v152, -v151, v158, v153
	v_cmp_ge_f32_e64 s[12:13], 0, v152
	v_add_u32_e32 v152, 1, v158
	v_lshlrev_b64 v[80:81], 10, v[200:201]
	v_cndmask_b32_e64 v151, v158, v151, s[12:13]
	v_fma_f32 v158, -v152, v158, v153
	v_cmp_lt_f32_e64 s[12:13], 0, v158
	v_rcp_f32_e32 v144, v144
	v_rcp_f32_e32 v145, v145
	v_cndmask_b32_e64 v151, v151, v152, s[12:13]
	v_add_f32_e32 v136, v136, v108
	v_mul_f32_e32 v136, 0xbfb8aa3b, v136
	v_lshl_add_u64 v[152:153], v[80:81], 0, v[180:181]
	v_lshlrev_b64 v[152:153], 1, v[152:153]
	v_exp_f32_e32 v136, v136
	v_cvt_pk_bf16_f32 v154, v154, v155
	v_cvt_pk_bf16_f32 v155, v156, v157
	v_lshl_add_u64 v[156:157], s[70:71], 0, v[152:153]
	global_store_dwordx2 v[156:157], v[154:155], off
	v_lshlrev_b32_e32 v154, 16, v68
	v_and_b32_e32 v155, 0xffff0000, v68
	v_pk_mul_f32 v[144:145], v[144:145], v[148:149]
	v_rcp_f32_e32 v146, v146
	v_rcp_f32_e32 v147, v147
	v_pk_mul_f32 v[144:145], v[144:145], v[154:155]
	v_add_f32_e32 v137, v137, v109
	v_cvt_pk_bf16_f32 v68, v144, v145
	v_lshlrev_b32_e32 v144, 16, v69
	v_and_b32_e32 v145, 0xffff0000, v69
	v_add_f32_e32 v69, 1.0, v136
	v_rcp_f32_e32 v136, v69
	v_pk_mul_f32 v[146:147], v[146:147], v[150:151]
	v_mul_f32_e32 v137, 0xbfb8aa3b, v137
	v_pk_mul_f32 v[144:145], v[146:147], v[144:145]
	v_mul_f32_e32 v146, v136, v162
	v_cvt_pk_bf16_f32 v69, v144, v145
	v_lshl_add_u64 v[144:145], s[68:69], 0, v[152:153]
	global_store_dwordx2 v[144:145], v[68:69], off
	v_add_f32_e32 v68, v146, v146
	v_mul_f32_e32 v68, 0x3fb8aa3b, v68
	v_exp_f32_e32 v68, v68
	v_add_f32_e32 v69, v140, v104
	v_mul_f32_e32 v69, 0xbfb8aa3b, v69
	v_exp_f32_e32 v136, v69
	v_sub_f32_e32 v68, 1.0, v68
	v_exp_f32_e32 v137, v137
	v_add_f32_e32 v138, v138, v110
	v_mov_b32_e32 v140, v68
; __device__ __forceinline__ float bflo(unsigned w) { return __uint_as_float(w << 16); }
; __device__ __forceinline__ float bfhi(unsigned w) { return __uint_as_float(w & 0xffff0000u); }
; __device__ __forceinline__ float sigmoidf_(float x) { return __builtin_amdgcn_rcpf(1.0f + __expf(-x)); }
;     __device__ __forceinline__ void operator()(AccRef acc, const Unit& u, int wr, int wc, int fr, int fq) const {
;     ...
;             for (int ai = 0; ai < 2; ++ai)
; #pragma unroll
;                 for (int m = 0; m < 4; ++m) { const size_t off = (size_t)(row0 + ai * 128 + m * 16) * D + col0 + 4 * n;
;                     float lo[4], bo[4];
; #pragma unroll
;                     for (int j = 0; j < 4; ++j) { const unsigned w = rws[ai][m][2 * n + (j >> 1)]; const float rec = (j & 1) ? bfhi(w) : bflo(w);
;                         const float r = sigmoidf_(acc[ai][0][m][n][j] + ba[j]), ig = sigmoidf_(acc[ai][1][m][n][j] + bx[j]);
;                         const float la = k8[j] * r; const float mult = __builtin_sqrtf(1.0f - __expf(2.0f * la));
;                         lo[j] = la; bo[j] = mult * ig * rec; }
;                     *(u32x2*)(LA + off) = (u32x2){cvt_pk_bf16(lo[0], lo[1]), cvt_pk_bf16(lo[2], lo[3])}; *(u32x2*)(BV + off) = (u32x2){cvt_pk_bf16(bo[0], bo[1]), cvt_pk_bf16(bo[2], bo[3])}; }
	v_sqrt_f32_e32 v144, v140
	v_add_f32_e32 v137, 1.0, v137
	v_rcp_f32_e32 v137, v137
	v_add_f32_e32 v141, v141, v105
	v_add_u32_e32 v145, -1, v144
	v_fma_f32 v147, -v145, v144, v140
	v_cmp_ge_f32_e64 s[12:13], 0, v147
	v_add_u32_e32 v147, 1, v144
	v_mul_f32_e32 v138, 0xbfb8aa3b, v138
	v_cndmask_b32_e64 v145, v144, v145, s[12:13]
	v_fma_f32 v144, -v147, v144, v140
	v_cmp_lt_f32_e64 s[12:13], 0, v144
	v_mul_f32_e32 v141, 0xbfb8aa3b, v141
	v_exp_f32_e32 v138, v138
	v_cndmask_b32_e64 v144, v145, v147, s[12:13]
	v_mul_f32_e32 v147, v137, v163
	v_add_f32_e32 v137, v147, v147
	v_mul_f32_e32 v137, 0x3fb8aa3b, v137
	v_exp_f32_e32 v137, v137
	v_exp_f32_e32 v141, v141
	v_sub_f32_e32 v137, 1.0, v137
	v_add_f32_e32 v138, 1.0, v138
	v_mov_b32_e32 v145, v137
	v_sqrt_f32_e32 v148, v145
	v_add_f32_e32 v137, 1.0, v141
	v_rcp_f32_e32 v138, v138
	v_mov_b32_e32 v140, v144
	v_add_u32_e32 v141, -1, v148
	v_fma_f32 v144, -v141, v148, v145
	v_cmp_ge_f32_e64 s[12:13], 0, v144
	v_add_u32_e32 v144, 1, v148
	v_add_f32_e32 v139, v139, v111
	v_cndmask_b32_e64 v141, v148, v141, s[12:13]
	v_fma_f32 v148, -v144, v148, v145
	v_cmp_lt_f32_e64 s[12:13], 0, v148
	v_mul_f32_e32 v148, v138, v160
	v_add_f32_e32 v138, v148, v148
	v_mul_f32_e32 v138, 0x3fb8aa3b, v138
	v_exp_f32_e32 v138, v138
	v_cndmask_b32_e64 v141, v141, v144, s[12:13]
	v_sub_f32_e32 v138, 1.0, v138
	v_add_f32_e32 v142, v142, v106
	v_mul_f32_e32 v139, 0xbfb8aa3b, v139
	v_mul_f32_e32 v142, 0xbfb8aa3b, v142
	v_mov_b32_e32 v144, v138
	v_exp_f32_e32 v139, v139
	v_exp_f32_e32 v142, v142
	v_sqrt_f32_e32 v149, v144
	v_add_f32_e32 v139, 1.0, v139
	v_add_f32_e32 v138, 1.0, v142
	v_add_u32_e32 v142, -1, v149
	v_rcp_f32_e32 v139, v139
	v_fma_f32 v145, -v142, v149, v144
	v_cmp_ge_f32_e64 s[12:13], 0, v145
	v_add_u32_e32 v145, 1, v149
	v_add_f32_e32 v143, v143, v107
	v_cndmask_b32_e64 v142, v149, v142, s[12:13]
	v_fma_f32 v149, -v145, v149, v144
	v_cmp_lt_f32_e64 s[12:13], 0, v149
	v_mul_f32_e32 v149, v139, v161
	v_add_f32_e32 v139, v149, v149
	v_mul_f32_e32 v139, 0x3fb8aa3b, v139
	v_exp_f32_e32 v139, v139
	v_cndmask_b32_e64 v142, v142, v145, s[12:13]
	v_sub_f32_e32 v139, 1.0, v139
	v_mul_f32_e32 v143, 0xbfb8aa3b, v143
	v_exp_f32_e32 v143, v143
	v_mov_b32_e32 v145, v139
	v_sqrt_f32_e32 v150, v145
	v_add_f32_e32 v139, 1.0, v143
	v_add_f32_e32 v136, 1.0, v136
	v_add_u32_e32 v143, -1, v150
	v_fma_f32 v144, -v143, v150, v145
	v_cmp_ge_f32_e64 s[12:13], 0, v144
	v_add_u32_e32 v144, 1, v150
	v_lshlrev_b64 v[68:69], 10, v[198:199]
	v_cndmask_b32_e64 v143, v150, v143, s[12:13]
	v_fma_f32 v150, -v144, v150, v145
	v_cmp_lt_f32_e64 s[12:13], 0, v150
	v_rcp_f32_e32 v136, v136
	v_rcp_f32_e32 v137, v137
	v_cndmask_b32_e64 v143, v143, v144, s[12:13]
	v_add_f32_e32 v128, v128, v108
	v_mul_f32_e32 v128, 0xbfb8aa3b, v128
	v_lshl_add_u64 v[144:145], v[68:69], 0, v[180:181]
	v_lshlrev_b64 v[144:145], 1, v[144:145]
	v_exp_f32_e32 v128, v128
	v_cvt_pk_bf16_f32 v146, v146, v147
	v_cvt_pk_bf16_f32 v147, v148, v149
	v_lshl_add_u64 v[148:149], s[70:71], 0, v[144:145]
	global_store_dwordx2 v[148:149], v[146:147], off
	v_lshlrev_b32_e32 v146, 16, v56
	v_and_b32_e32 v147, 0xffff0000, v56
	v_pk_mul_f32 v[136:137], v[136:137], v[140:141]
	v_rcp_f32_e32 v138, v138
	v_rcp_f32_e32 v139, v139
	v_pk_mul_f32 v[136:137], v[136:137], v[146:147]
	v_add_f32_e32 v129, v129, v109
	v_cvt_pk_bf16_f32 v56, v136, v137
	v_lshlrev_b32_e32 v136, 16, v57
	v_and_b32_e32 v137, 0xffff0000, v57
	v_add_f32_e32 v57, 1.0, v128
	v_rcp_f32_e32 v128, v57
	v_pk_mul_f32 v[138:139], v[138:139], v[142:143]
	v_mul_f32_e32 v129, 0xbfb8aa3b, v129
	v_pk_mul_f32 v[136:137], v[138:139], v[136:137]
	v_mul_f32_e32 v138, v128, v162
	v_cvt_pk_bf16_f32 v57, v136, v137
	v_lshl_add_u64 v[136:137], s[68:69], 0, v[144:145]
	global_store_dwordx2 v[136:137], v[56:57], off
	v_add_f32_e32 v56, v138, v138
	v_mul_f32_e32 v56, 0x3fb8aa3b, v56
	v_exp_f32_e32 v56, v56
	v_add_f32_e32 v57, v132, v104
	v_mul_f32_e32 v57, 0xbfb8aa3b, v57
	v_exp_f32_e32 v128, v57
	v_sub_f32_e32 v56, 1.0, v56
	v_exp_f32_e32 v129, v129
	v_add_f32_e32 v130, v130, v110
	v_mov_b32_e32 v132, v56
	v_sqrt_f32_e32 v136, v132
	v_add_f32_e32 v129, 1.0, v129
	v_rcp_f32_e32 v129, v129
	v_add_f32_e32 v133, v133, v105
	v_add_u32_e32 v137, -1, v136
	v_fma_f32 v139, -v137, v136, v132
	v_cmp_ge_f32_e64 s[12:13], 0, v139
	v_add_u32_e32 v139, 1, v136
	v_mul_f32_e32 v130, 0xbfb8aa3b, v130
	v_cndmask_b32_e64 v137, v136, v137, s[12:13]
	v_fma_f32 v136, -v139, v136, v132
	v_cmp_lt_f32_e64 s[12:13], 0, v136
	v_mul_f32_e32 v133, 0xbfb8aa3b, v133
	v_exp_f32_e32 v130, v130
	v_cndmask_b32_e64 v136, v137, v139, s[12:13]
	v_mul_f32_e32 v139, v129, v163
	v_add_f32_e32 v129, v139, v139
	v_mul_f32_e32 v129, 0x3fb8aa3b, v129
	v_exp_f32_e32 v129, v129
	v_exp_f32_e32 v133, v133
	v_sub_f32_e32 v129, 1.0, v129
	v_add_f32_e32 v130, 1.0, v130
	v_mov_b32_e32 v137, v129
	v_sqrt_f32_e32 v140, v137
	v_add_f32_e32 v129, 1.0, v133
	v_rcp_f32_e32 v130, v130
	v_mov_b32_e32 v132, v136
	v_add_u32_e32 v133, -1, v140
	v_fma_f32 v136, -v133, v140, v137
	v_cmp_ge_f32_e64 s[12:13], 0, v136
	v_add_u32_e32 v136, 1, v140
	v_add_f32_e32 v131, v131, v111
	v_cndmask_b32_e64 v133, v140, v133, s[12:13]
	v_fma_f32 v140, -v136, v140, v137
	v_cmp_lt_f32_e64 s[12:13], 0, v140
	v_mul_f32_e32 v140, v130, v160
	v_add_f32_e32 v130, v140, v140
	v_mul_f32_e32 v130, 0x3fb8aa3b, v130
	v_exp_f32_e32 v130, v130
	v_cndmask_b32_e64 v133, v133, v136, s[12:13]
	v_sub_f32_e32 v130, 1.0, v130
	v_add_f32_e32 v134, v134, v106
	v_mul_f32_e32 v131, 0xbfb8aa3b, v131
	v_mul_f32_e32 v134, 0xbfb8aa3b, v134
	v_mov_b32_e32 v136, v130
	v_exp_f32_e32 v131, v131
	v_exp_f32_e32 v134, v134
	v_sqrt_f32_e32 v141, v136
; __device__ __forceinline__ float bflo(unsigned w) { return __uint_as_float(w << 16); }
; __device__ __forceinline__ float bfhi(unsigned w) { return __uint_as_float(w & 0xffff0000u); }
; __device__ __forceinline__ float sigmoidf_(float x) { return __builtin_amdgcn_rcpf(1.0f + __expf(-x)); }
;     __device__ __forceinline__ void operator()(AccRef acc, const Unit& u, int wr, int wc, int fr, int fq) const {
;     ...
;             for (int ai = 0; ai < 2; ++ai)
; #pragma unroll
;                 for (int m = 0; m < 4; ++m) { const size_t off = (size_t)(row0 + ai * 128 + m * 16) * D + col0 + 4 * n;
;                     float lo[4], bo[4];
; #pragma unroll
;                     for (int j = 0; j < 4; ++j) { const unsigned w = rws[ai][m][2 * n + (j >> 1)]; const float rec = (j & 1) ? bfhi(w) : bflo(w);
;                         const float r = sigmoidf_(acc[ai][0][m][n][j] + ba[j]), ig = sigmoidf_(acc[ai][1][m][n][j] + bx[j]);
;                         const float la = k8[j] * r; const float mult = __builtin_sqrtf(1.0f - __expf(2.0f * la));
;                         lo[j] = la; bo[j] = mult * ig * rec; }
;                     *(u32x2*)(LA + off) = (u32x2){cvt_pk_bf16(lo[0], lo[1]), cvt_pk_bf16(lo[2], lo[3])}; *(u32x2*)(BV + off) = (u32x2){cvt_pk_bf16(bo[0], bo[1]), cvt_pk_bf16(bo[2], bo[3])}; }
	v_add_f32_e32 v131, 1.0, v131
	v_add_f32_e32 v130, 1.0, v134
	v_add_u32_e32 v134, -1, v141
	v_rcp_f32_e32 v131, v131
	v_fma_f32 v137, -v134, v141, v136
	v_cmp_ge_f32_e64 s[12:13], 0, v137
	v_add_u32_e32 v137, 1, v141
	v_add_f32_e32 v135, v135, v107
	v_cndmask_b32_e64 v134, v141, v134, s[12:13]
	v_fma_f32 v141, -v137, v141, v136
	v_cmp_lt_f32_e64 s[12:13], 0, v141
	v_mul_f32_e32 v141, v131, v161
	v_add_f32_e32 v131, v141, v141
	v_mul_f32_e32 v131, 0x3fb8aa3b, v131
	v_exp_f32_e32 v131, v131
	v_cndmask_b32_e64 v134, v134, v137, s[12:13]
	v_sub_f32_e32 v131, 1.0, v131
	v_mul_f32_e32 v135, 0xbfb8aa3b, v135
	v_exp_f32_e32 v135, v135
	v_mov_b32_e32 v137, v131
	v_sqrt_f32_e32 v142, v137
	v_add_f32_e32 v131, 1.0, v135
	v_add_f32_e32 v128, 1.0, v128
	v_add_u32_e32 v135, -1, v142
	v_fma_f32 v136, -v135, v142, v137
	v_cmp_ge_f32_e64 s[12:13], 0, v136
	v_add_u32_e32 v136, 1, v142
	v_lshlrev_b64 v[56:57], 10, v[196:197]
	v_cndmask_b32_e64 v135, v142, v135, s[12:13]
	v_fma_f32 v142, -v136, v142, v137
	v_cmp_lt_f32_e64 s[12:13], 0, v142
	v_rcp_f32_e32 v128, v128
	v_rcp_f32_e32 v129, v129
	v_cndmask_b32_e64 v135, v135, v136, s[12:13]
	v_add_f32_e32 v120, v120, v108
	v_mul_f32_e32 v120, 0xbfb8aa3b, v120
	v_lshl_add_u64 v[136:137], v[56:57], 0, v[180:181]
	v_lshlrev_b64 v[136:137], 1, v[136:137]
	v_exp_f32_e32 v120, v120
	v_cvt_pk_bf16_f32 v138, v138, v139
	v_cvt_pk_bf16_f32 v139, v140, v141
	v_lshl_add_u64 v[140:141], s[70:71], 0, v[136:137]
	global_store_dwordx2 v[140:141], v[138:139], off
	v_lshlrev_b32_e32 v138, 16, v44
	v_and_b32_e32 v139, 0xffff0000, v44
	v_pk_mul_f32 v[128:129], v[128:129], v[132:133]
	v_rcp_f32_e32 v130, v130
	v_rcp_f32_e32 v131, v131
	v_pk_mul_f32 v[128:129], v[128:129], v[138:139]
	v_add_f32_e32 v121, v121, v109
	v_cvt_pk_bf16_f32 v44, v128, v129
	v_lshlrev_b32_e32 v128, 16, v45
	v_and_b32_e32 v129, 0xffff0000, v45
	v_add_f32_e32 v45, 1.0, v120
	v_rcp_f32_e32 v120, v45
	v_pk_mul_f32 v[130:131], v[130:131], v[134:135]
	v_mul_f32_e32 v121, 0xbfb8aa3b, v121
	v_pk_mul_f32 v[128:129], v[130:131], v[128:129]
	v_mul_f32_e32 v130, v120, v162
	v_cvt_pk_bf16_f32 v45, v128, v129
	v_lshl_add_u64 v[128:129], s[68:69], 0, v[136:137]
	global_store_dwordx2 v[128:129], v[44:45], off
	v_add_f32_e32 v44, v130, v130
	v_mul_f32_e32 v44, 0x3fb8aa3b, v44
	v_exp_f32_e32 v44, v44
	v_add_f32_e32 v45, v124, v104
	v_mul_f32_e32 v45, 0xbfb8aa3b, v45
	v_exp_f32_e32 v120, v45
	v_sub_f32_e32 v44, 1.0, v44
	v_exp_f32_e32 v121, v121
	v_add_f32_e32 v122, v122, v110
	v_mov_b32_e32 v124, v44
	v_sqrt_f32_e32 v128, v124
	v_add_f32_e32 v121, 1.0, v121
	v_rcp_f32_e32 v121, v121
	v_add_f32_e32 v125, v125, v105
	v_add_u32_e32 v129, -1, v128
	v_fma_f32 v131, -v129, v128, v124
	v_cmp_ge_f32_e64 s[12:13], 0, v131
	v_add_u32_e32 v131, 1, v128
	v_mul_f32_e32 v122, 0xbfb8aa3b, v122
	v_cndmask_b32_e64 v129, v128, v129, s[12:13]
	v_fma_f32 v128, -v131, v128, v124
	v_cmp_lt_f32_e64 s[12:13], 0, v128
	v_mul_f32_e32 v125, 0xbfb8aa3b, v125
	v_exp_f32_e32 v122, v122
	v_cndmask_b32_e64 v128, v129, v131, s[12:13]
	v_mul_f32_e32 v131, v121, v163
	v_add_f32_e32 v121, v131, v131
	v_mul_f32_e32 v121, 0x3fb8aa3b, v121
	v_exp_f32_e32 v121, v121
	v_exp_f32_e32 v125, v125
	v_sub_f32_e32 v121, 1.0, v121
	v_add_f32_e32 v122, 1.0, v122
	v_mov_b32_e32 v129, v121
	v_sqrt_f32_e32 v132, v129
	v_add_f32_e32 v121, 1.0, v125
	v_rcp_f32_e32 v122, v122
	v_mov_b32_e32 v124, v128
	v_add_u32_e32 v125, -1, v132
	v_fma_f32 v128, -v125, v132, v129
	v_cmp_ge_f32_e64 s[12:13], 0, v128
	v_add_u32_e32 v128, 1, v132
	v_add_f32_e32 v123, v123, v111
	v_cndmask_b32_e64 v125, v132, v125, s[12:13]
	v_fma_f32 v132, -v128, v132, v129
	v_cmp_lt_f32_e64 s[12:13], 0, v132
	v_mul_f32_e32 v132, v122, v160
	v_add_f32_e32 v122, v132, v132
	v_mul_f32_e32 v122, 0x3fb8aa3b, v122
	v_exp_f32_e32 v122, v122
	v_cndmask_b32_e64 v125, v125, v128, s[12:13]
	v_sub_f32_e32 v122, 1.0, v122
	v_add_f32_e32 v126, v126, v106
	v_mul_f32_e32 v123, 0xbfb8aa3b, v123
	v_mul_f32_e32 v126, 0xbfb8aa3b, v126
	v_mov_b32_e32 v128, v122
	v_exp_f32_e32 v123, v123
	v_exp_f32_e32 v126, v126
	v_sqrt_f32_e32 v133, v128
	v_add_f32_e32 v123, 1.0, v123
	v_add_f32_e32 v122, 1.0, v126
	v_add_u32_e32 v126, -1, v133
	v_rcp_f32_e32 v123, v123
	v_fma_f32 v129, -v126, v133, v128
	v_cmp_ge_f32_e64 s[12:13], 0, v129
	v_add_u32_e32 v129, 1, v133
	v_add_f32_e32 v127, v127, v107
	v_cndmask_b32_e64 v126, v133, v126, s[12:13]
	v_fma_f32 v133, -v129, v133, v128
	v_cmp_lt_f32_e64 s[12:13], 0, v133
	v_mul_f32_e32 v133, v123, v161
	v_add_f32_e32 v123, v133, v133
	v_mul_f32_e32 v123, 0x3fb8aa3b, v123
	v_exp_f32_e32 v123, v123
	v_cndmask_b32_e64 v126, v126, v129, s[12:13]
	v_sub_f32_e32 v123, 1.0, v123
	v_mul_f32_e32 v127, 0xbfb8aa3b, v127
	v_exp_f32_e32 v127, v127
	v_mov_b32_e32 v129, v123
	v_sqrt_f32_e32 v134, v129
	v_add_f32_e32 v123, 1.0, v127
	v_add_f32_e32 v120, 1.0, v120
	v_add_u32_e32 v127, -1, v134
	v_fma_f32 v128, -v127, v134, v129
	v_cmp_ge_f32_e64 s[12:13], 0, v128
	v_add_u32_e32 v128, 1, v134
	v_lshlrev_b64 v[44:45], 10, v[194:195]
	v_cndmask_b32_e64 v127, v134, v127, s[12:13]
	v_fma_f32 v134, -v128, v134, v129
	v_cmp_lt_f32_e64 s[12:13], 0, v134
	v_rcp_f32_e32 v120, v120
	v_rcp_f32_e32 v121, v121
	v_cndmask_b32_e64 v127, v127, v128, s[12:13]
	v_add_f32_e32 v112, v112, v108
	v_mul_f32_e32 v112, 0xbfb8aa3b, v112
	v_lshl_add_u64 v[128:129], v[44:45], 0, v[180:181]
	v_lshlrev_b64 v[128:129], 1, v[128:129]
	v_exp_f32_e32 v112, v112
	v_cvt_pk_bf16_f32 v130, v130, v131
	v_cvt_pk_bf16_f32 v131, v132, v133
	v_lshl_add_u64 v[132:133], s[70:71], 0, v[128:129]
	global_store_dwordx2 v[132:133], v[130:131], off
	v_lshlrev_b32_e32 v130, 16, v32
	v_and_b32_e32 v131, 0xffff0000, v32
; __device__ __forceinline__ float bflo(unsigned w) { return __uint_as_float(w << 16); }
; __device__ __forceinline__ float bfhi(unsigned w) { return __uint_as_float(w & 0xffff0000u); }
; __device__ __forceinline__ float sigmoidf_(float x) { return __builtin_amdgcn_rcpf(1.0f + __expf(-x)); }
;     __device__ __forceinline__ void operator()(AccRef acc, const Unit& u, int wr, int wc, int fr, int fq) const {
;     ...
;             for (int ai = 0; ai < 2; ++ai)
; #pragma unroll
;                 for (int m = 0; m < 4; ++m) { const size_t off = (size_t)(row0 + ai * 128 + m * 16) * D + col0 + 4 * n;
;                     float lo[4], bo[4];
; #pragma unroll
;                     for (int j = 0; j < 4; ++j) { const unsigned w = rws[ai][m][2 * n + (j >> 1)]; const float rec = (j & 1) ? bfhi(w) : bflo(w);
;                         const float r = sigmoidf_(acc[ai][0][m][n][j] + ba[j]), ig = sigmoidf_(acc[ai][1][m][n][j] + bx[j]);
;                         const float la = k8[j] * r; const float mult = __builtin_sqrtf(1.0f - __expf(2.0f * la));
;                         lo[j] = la; bo[j] = mult * ig * rec; }
;                     *(u32x2*)(LA + off) = (u32x2){cvt_pk_bf16(lo[0], lo[1]), cvt_pk_bf16(lo[2], lo[3])}; *(u32x2*)(BV + off) = (u32x2){cvt_pk_bf16(bo[0], bo[1]), cvt_pk_bf16(bo[2], bo[3])}; }
	v_pk_mul_f32 v[120:121], v[120:121], v[124:125]
	v_rcp_f32_e32 v122, v122
	v_rcp_f32_e32 v123, v123
	v_pk_mul_f32 v[120:121], v[120:121], v[130:131]
	v_add_f32_e32 v113, v113, v109
	v_cvt_pk_bf16_f32 v32, v120, v121
	v_lshlrev_b32_e32 v120, 16, v33
	v_and_b32_e32 v121, 0xffff0000, v33
	v_add_f32_e32 v33, 1.0, v112
	v_rcp_f32_e32 v112, v33
	v_pk_mul_f32 v[122:123], v[122:123], v[126:127]
	v_mul_f32_e32 v113, 0xbfb8aa3b, v113
	v_pk_mul_f32 v[120:121], v[122:123], v[120:121]
	v_mul_f32_e32 v122, v112, v162
	v_cvt_pk_bf16_f32 v33, v120, v121
	v_lshl_add_u64 v[120:121], s[68:69], 0, v[128:129]
	global_store_dwordx2 v[120:121], v[32:33], off
	v_add_f32_e32 v32, v122, v122
	v_mul_f32_e32 v32, 0x3fb8aa3b, v32
	v_exp_f32_e32 v32, v32
	v_add_f32_e32 v33, v116, v104
	v_mul_f32_e32 v33, 0xbfb8aa3b, v33
	v_exp_f32_e32 v112, v33
	v_sub_f32_e32 v32, 1.0, v32
	v_exp_f32_e32 v113, v113
	v_add_f32_e32 v114, v114, v110
	v_mov_b32_e32 v116, v32
	v_sqrt_f32_e32 v120, v116
	v_add_f32_e32 v113, 1.0, v113
	v_rcp_f32_e32 v113, v113
	v_add_f32_e32 v117, v117, v105
	v_add_u32_e32 v121, -1, v120
	v_fma_f32 v123, -v121, v120, v116
	v_cmp_ge_f32_e64 s[12:13], 0, v123
	v_add_u32_e32 v123, 1, v120
	v_mul_f32_e32 v114, 0xbfb8aa3b, v114
	v_cndmask_b32_e64 v121, v120, v121, s[12:13]
	v_fma_f32 v120, -v123, v120, v116
	v_cmp_lt_f32_e64 s[12:13], 0, v120
	v_mul_f32_e32 v117, 0xbfb8aa3b, v117
	v_exp_f32_e32 v114, v114
	v_cndmask_b32_e64 v120, v121, v123, s[12:13]
	v_mul_f32_e32 v123, v113, v163
	v_add_f32_e32 v113, v123, v123
	v_mul_f32_e32 v113, 0x3fb8aa3b, v113
	v_exp_f32_e32 v113, v113
	v_exp_f32_e32 v117, v117
	v_sub_f32_e32 v113, 1.0, v113
	v_add_f32_e32 v114, 1.0, v114
	v_mov_b32_e32 v121, v113
	v_sqrt_f32_e32 v124, v121
	v_add_f32_e32 v113, 1.0, v117
	v_rcp_f32_e32 v114, v114
	v_mov_b32_e32 v116, v120
	v_add_u32_e32 v117, -1, v124
	v_fma_f32 v120, -v117, v124, v121
	v_cmp_ge_f32_e64 s[12:13], 0, v120
	v_add_u32_e32 v120, 1, v124
	v_add_f32_e32 v115, v115, v111
	v_cndmask_b32_e64 v117, v124, v117, s[12:13]
	v_fma_f32 v124, -v120, v124, v121
	v_cmp_lt_f32_e64 s[12:13], 0, v124
	v_mul_f32_e32 v124, v114, v160
	v_add_f32_e32 v114, v124, v124
	v_mul_f32_e32 v114, 0x3fb8aa3b, v114
	v_exp_f32_e32 v114, v114
	v_cndmask_b32_e64 v117, v117, v120, s[12:13]
	v_sub_f32_e32 v114, 1.0, v114
	v_add_f32_e32 v118, v118, v106
	v_mul_f32_e32 v115, 0xbfb8aa3b, v115
	v_mul_f32_e32 v118, 0xbfb8aa3b, v118
	v_mov_b32_e32 v120, v114
	v_exp_f32_e32 v115, v115
	v_exp_f32_e32 v118, v118
	v_sqrt_f32_e32 v125, v120
	v_add_f32_e32 v115, 1.0, v115
	v_add_f32_e32 v114, 1.0, v118
	v_add_u32_e32 v118, -1, v125
	v_rcp_f32_e32 v115, v115
	v_fma_f32 v121, -v118, v125, v120
	v_cmp_ge_f32_e64 s[12:13], 0, v121
	v_add_u32_e32 v121, 1, v125
	v_add_f32_e32 v119, v119, v107
	v_cndmask_b32_e64 v118, v125, v118, s[12:13]
	v_fma_f32 v125, -v121, v125, v120
	v_cmp_lt_f32_e64 s[12:13], 0, v125
	v_mul_f32_e32 v125, v115, v161
	v_add_f32_e32 v115, v125, v125
	v_mul_f32_e32 v115, 0x3fb8aa3b, v115
	v_exp_f32_e32 v115, v115
	v_cndmask_b32_e64 v118, v118, v121, s[12:13]
	v_sub_f32_e32 v115, 1.0, v115
	v_mul_f32_e32 v119, 0xbfb8aa3b, v119
	v_exp_f32_e32 v119, v119
	v_mov_b32_e32 v121, v115
	v_sqrt_f32_e32 v126, v121
	v_add_f32_e32 v115, 1.0, v119
	v_add_f32_e32 v112, 1.0, v112
	v_add_u32_e32 v119, -1, v126
	v_fma_f32 v120, -v119, v126, v121
	v_cmp_ge_f32_e64 s[12:13], 0, v120
	v_add_u32_e32 v120, 1, v126
	v_lshlrev_b64 v[32:33], 10, v[192:193]
	v_cndmask_b32_e64 v119, v126, v119, s[12:13]
	v_fma_f32 v126, -v120, v126, v121
	v_cmp_lt_f32_e64 s[12:13], 0, v126
	v_rcp_f32_e32 v112, v112
	v_rcp_f32_e32 v113, v113
	v_cndmask_b32_e64 v119, v119, v120, s[12:13]
	v_add_f32_e32 v96, v96, v108
	v_mul_f32_e32 v96, 0xbfb8aa3b, v96
	v_lshl_add_u64 v[120:121], v[32:33], 0, v[180:181]
	v_lshlrev_b64 v[120:121], 1, v[120:121]
	v_exp_f32_e32 v96, v96
	v_cvt_pk_bf16_f32 v122, v122, v123
	v_cvt_pk_bf16_f32 v123, v124, v125
	v_lshl_add_u64 v[124:125], s[70:71], 0, v[120:121]
	global_store_dwordx2 v[124:125], v[122:123], off
	v_lshlrev_b32_e32 v122, 16, v20
	v_and_b32_e32 v123, 0xffff0000, v20
	v_pk_mul_f32 v[112:113], v[112:113], v[116:117]
	v_rcp_f32_e32 v114, v114
	v_rcp_f32_e32 v115, v115
	v_pk_mul_f32 v[112:113], v[112:113], v[122:123]
	v_add_f32_e32 v97, v97, v109
	v_cvt_pk_bf16_f32 v20, v112, v113
	v_lshlrev_b32_e32 v112, 16, v21
	v_and_b32_e32 v113, 0xffff0000, v21
	v_add_f32_e32 v21, 1.0, v96
	v_rcp_f32_e32 v96, v21
	v_pk_mul_f32 v[114:115], v[114:115], v[118:119]
	v_mul_f32_e32 v97, 0xbfb8aa3b, v97
	v_pk_mul_f32 v[112:113], v[114:115], v[112:113]
	v_mul_f32_e32 v108, v96, v162
	v_cvt_pk_bf16_f32 v21, v112, v113
	v_lshl_add_u64 v[112:113], s[68:69], 0, v[120:121]
	global_store_dwordx2 v[112:113], v[20:21], off
	v_add_f32_e32 v20, v108, v108
	v_mul_f32_e32 v20, 0x3fb8aa3b, v20
	v_exp_f32_e32 v20, v20
	v_add_f32_e32 v21, v100, v104
	v_mul_f32_e32 v21, 0xbfb8aa3b, v21
	v_exp_f32_e32 v96, v21
	v_sub_f32_e32 v20, 1.0, v20
	v_exp_f32_e32 v97, v97
	v_add_f32_e32 v98, v98, v110
	v_mov_b32_e32 v100, v20
	v_sqrt_f32_e32 v104, v100
	v_add_f32_e32 v97, 1.0, v97
	v_rcp_f32_e32 v97, v97
	v_add_f32_e32 v101, v101, v105
	v_add_u32_e32 v112, -1, v104
	v_fma_f32 v113, -v112, v104, v100
	v_cmp_ge_f32_e64 s[12:13], 0, v113
	v_mul_f32_e32 v98, 0xbfb8aa3b, v98
	v_mul_f32_e32 v101, 0xbfb8aa3b, v101
	v_cndmask_b32_e64 v109, v104, v112, s[12:13]
	v_add_u32_e32 v112, 1, v104
	v_fma_f32 v104, -v112, v104, v100
	v_cmp_lt_f32_e64 s[12:13], 0, v104
	v_exp_f32_e32 v98, v98
	v_exp_f32_e32 v101, v101
	v_cndmask_b32_e64 v104, v109, v112, s[12:13]
	v_mul_f32_e32 v109, v97, v163
	v_add_f32_e32 v97, v109, v109
	v_mul_f32_e32 v97, 0x3fb8aa3b, v97
	v_exp_f32_e32 v97, v97
; __device__ __forceinline__ float bflo(unsigned w) { return __uint_as_float(w << 16); }
; __device__ __forceinline__ float bfhi(unsigned w) { return __uint_as_float(w & 0xffff0000u); }
; __device__ __forceinline__ float sigmoidf_(float x) { return __builtin_amdgcn_rcpf(1.0f + __expf(-x)); }
;     __device__ __forceinline__ void operator()(AccRef acc, const Unit& u, int wr, int wc, int fr, int fq) const {
;     ...
;             const f32x4 ba = *(const f32x4*)(b_a + col0 + 4 * n), bx = *(const f32x4*)(b_x + col0 + 4 * n), l = *(const f32x4*)(lam + col0 + 4 * n);
;             f32x4 k8;
; #pragma unroll
;             for (int j = 0; j < 4; ++j) k8[j] = -8.0f * __logf(1.0f + __expf(-l[j]));
;     ...
;                     for (int j = 0; j < 4; ++j) { const unsigned w = rws[ai][m][2 * n + (j >> 1)]; const float rec = (j & 1) ? bfhi(w) : bflo(w);
;                         const float r = sigmoidf_(acc[ai][0][m][n][j] + ba[j]), ig = sigmoidf_(acc[ai][1][m][n][j] + bx[j]);
;                         const float la = k8[j] * r; const float mult = __builtin_sqrtf(1.0f - __expf(2.0f * la));
;                         lo[j] = la; bo[j] = mult * ig * rec; }
;                     *(u32x2*)(LA + off) = (u32x2){cvt_pk_bf16(lo[0], lo[1]), cvt_pk_bf16(lo[2], lo[3])}; *(u32x2*)(BV + off) = (u32x2){cvt_pk_bf16(bo[0], bo[1]), cvt_pk_bf16(bo[2], bo[3])}; }
	v_add_f32_e32 v98, 1.0, v98
	v_rcp_f32_e32 v98, v98
	v_sub_f32_e32 v97, 1.0, v97
	v_mov_b32_e32 v100, v104
	v_add_f32_e32 v99, v99, v111
	v_mov_b32_e32 v105, v97
	v_sqrt_f32_e32 v112, v105
	v_add_f32_e32 v97, 1.0, v101
	v_mul_f32_e32 v99, 0xbfb8aa3b, v99
	v_exp_f32_e32 v99, v99
	v_add_u32_e32 v101, -1, v112
	v_fma_f32 v104, -v101, v112, v105
	v_cmp_ge_f32_e64 s[12:13], 0, v104
	v_add_u32_e32 v104, 1, v112
	v_fma_f32 v110, -v104, v112, v105
	v_cndmask_b32_e64 v101, v112, v101, s[12:13]
	v_cmp_lt_f32_e64 s[12:13], 0, v110
	v_mul_f32_e32 v110, v98, v160
	v_add_f32_e32 v98, v110, v110
	v_mul_f32_e32 v98, 0x3fb8aa3b, v98
	v_exp_f32_e32 v98, v98
	v_cndmask_b32_e64 v101, v101, v104, s[12:13]
	v_sub_f32_e32 v98, 1.0, v98
	v_add_f32_e32 v102, v102, v106
	v_add_f32_e32 v99, 1.0, v99
	v_mul_f32_e32 v102, 0xbfb8aa3b, v102
	v_mov_b32_e32 v104, v98
	v_rcp_f32_e32 v99, v99
	v_exp_f32_e32 v102, v102
	v_sqrt_f32_e32 v106, v104
	v_mul_f32_e32 v111, v99, v161
	v_add_f32_e32 v98, 1.0, v102
	v_add_u32_e32 v102, -1, v106
	v_add_f32_e32 v99, v111, v111
	v_fma_f32 v105, -v102, v106, v104
	v_mul_f32_e32 v99, 0x3fb8aa3b, v99
	v_cmp_ge_f32_e64 s[12:13], 0, v105
	v_add_u32_e32 v105, 1, v106
	v_exp_f32_e32 v99, v99
	v_cndmask_b32_e64 v102, v106, v102, s[12:13]
	v_fma_f32 v106, -v105, v106, v104
	v_cmp_lt_f32_e64 s[12:13], 0, v106
	v_sub_f32_e32 v99, 1.0, v99
	v_add_f32_e32 v103, v103, v107
	v_cndmask_b32_e64 v102, v102, v105, s[12:13]
	v_mul_f32_e32 v103, 0xbfb8aa3b, v103
	v_exp_f32_e32 v103, v103
	v_mov_b32_e32 v105, v99
	v_sqrt_f32_e32 v106, v105
	v_add_f32_e32 v99, 1.0, v103
	v_add_f32_e32 v96, 1.0, v96
	v_add_u32_e32 v103, -1, v106
	v_fma_f32 v104, -v103, v106, v105
	v_cmp_ge_f32_e64 s[12:13], 0, v104
	v_add_u32_e32 v104, 1, v106
	v_lshlrev_b64 v[20:21], 10, v[190:191]
	v_cndmask_b32_e64 v103, v106, v103, s[12:13]
	v_fma_f32 v106, -v104, v106, v105
	v_cmp_lt_f32_e64 s[12:13], 0, v106
	v_rcp_f32_e32 v96, v96
	v_rcp_f32_e32 v97, v97
	v_cndmask_b32_e64 v103, v103, v104, s[12:13]
	v_rcp_f32_e32 v98, v98
	v_rcp_f32_e32 v99, v99
	v_lshl_add_u64 v[104:105], v[20:21], 0, v[180:181]
	v_lshlrev_b64 v[104:105], 1, v[104:105]
	v_cvt_pk_bf16_f32 v106, v108, v109
	v_cvt_pk_bf16_f32 v107, v110, v111
	v_lshl_add_u64 v[108:109], s[70:71], 0, v[104:105]
	global_store_dwordx2 v[108:109], v[106:107], off
	v_lshlrev_b32_e32 v106, 16, v8
	v_and_b32_e32 v107, 0xffff0000, v8
	v_pk_mul_f32 v[96:97], v[96:97], v[100:101]
	v_pk_mul_f32 v[98:99], v[98:99], v[102:103]
	v_pk_mul_f32 v[96:97], v[96:97], v[106:107]
	v_or_b32_e32 v180, 4, v180
	v_cvt_pk_bf16_f32 v8, v96, v97
	v_lshlrev_b32_e32 v96, 16, v9
	v_and_b32_e32 v97, 0xffff0000, v9
	v_pk_mul_f32 v[96:97], v[98:99], v[96:97]
	v_lshl_add_u64 v[108:109], v[182:183], 0, v[180:181]
	v_cvt_pk_bf16_f32 v9, v96, v97
	v_lshl_add_u64 v[96:97], s[68:69], 0, v[104:105]
	global_store_dwordx2 v[96:97], v[8:9], off
	global_load_dwordx4 v[104:107], v[184:185], off offset:16
	global_load_dwordx4 v[100:103], v[186:187], off offset:16
	s_nop 0
	global_load_dwordx4 v[96:99], v[188:189], off offset:16
	s_mov_b64 s[16:17], s[44:45]
	s_waitcnt vmcnt(0)
	v_mul_f32_e32 v8, 0xbfb8aa3b, v104
	v_exp_f32_e32 v8, v8
	v_mul_f32_e32 v104, 0xbfb8aa3b, v105
	v_exp_f32_e32 v104, v104
	v_add_f32_e32 v84, v84, v100
	v_add_f32_e32 v8, 1.0, v8
	v_cmp_gt_f32_e32 vcc, s77, v8
	v_add_f32_e32 v104, 1.0, v104
	v_cmp_gt_f32_e64 s[12:13], s77, v104
	v_cndmask_b32_e64 v9, 0, 32, vcc
	v_ldexp_f32 v8, v8, v9
	v_log_f32_e32 v8, v8
	v_cndmask_b32_e64 v105, 0, 32, s[12:13]
	v_ldexp_f32 v104, v104, v105
	v_mul_f32_e32 v105, 0xbfb8aa3b, v106
	v_exp_f32_e32 v105, v105
	v_mul_f32_e32 v9, 0x3f317217, v8
	v_fma_f32 v9, v8, s78, -v9
	v_fmac_f32_e32 v9, 0x3377d1cf, v8
	v_fmac_f32_e32 v9, 0x3f317217, v8
	v_cmp_lt_f32_e64 s[14:15], |v8|, s79
	v_add_f32_e32 v105, 1.0, v105
	v_log_f32_e32 v104, v104
	v_cndmask_b32_e64 v8, v8, v9, s[14:15]
	v_cndmask_b32_e32 v9, 0, v210, vcc
	v_cmp_gt_f32_e32 vcc, s77, v105
	v_sub_f32_e32 v8, v8, v9
	v_mul_f32_e32 v9, 0x3f317217, v104
	v_cndmask_b32_e64 v106, 0, 32, vcc
	v_ldexp_f32 v105, v105, v106
	v_mul_f32_e32 v106, 0xbfb8aa3b, v107
	v_exp_f32_e32 v106, v106
	v_fma_f32 v9, v104, s78, -v9
	v_fmac_f32_e32 v9, 0x3377d1cf, v104
	v_log_f32_e32 v105, v105
	v_fmac_f32_e32 v9, 0x3f317217, v104
	v_cmp_lt_f32_e64 s[14:15], |v104|, s79
	v_add_f32_e32 v106, 1.0, v106
	v_mul_f32_e32 v84, 0xbfb8aa3b, v84
	v_cndmask_b32_e64 v9, v104, v9, s[14:15]
	v_cndmask_b32_e64 v104, 0, v210, s[12:13]
	v_cmp_gt_f32_e64 s[12:13], s77, v106
	v_sub_f32_e32 v9, v9, v104
	v_mul_f32_e32 v104, 0x3f317217, v105
	v_cndmask_b32_e64 v107, 0, 32, s[12:13]
	v_ldexp_f32 v106, v106, v107
	v_fma_f32 v104, v105, s78, -v104
	v_log_f32_e32 v106, v106
	v_fmac_f32_e32 v104, 0x3377d1cf, v105
	v_fmac_f32_e32 v104, 0x3f317217, v105
	v_cmp_lt_f32_e64 s[14:15], |v105|, s79
	v_add_f32_e32 v88, v88, v96
	v_exp_f32_e32 v84, v84
	v_cndmask_b32_e64 v104, v105, v104, s[14:15]
	v_cndmask_b32_e32 v105, 0, v210, vcc
	v_sub_f32_e32 v104, v104, v105
	v_mul_f32_e32 v105, 0x3f317217, v106
	v_fma_f32 v105, v106, s78, -v105
	v_fmac_f32_e32 v105, 0x3377d1cf, v106
	v_fmac_f32_e32 v105, 0x3f317217, v106
	v_cmp_lt_f32_e64 vcc, |v106|, s79
	v_mul_f32_e32 v88, 0xbfb8aa3b, v88
	v_add_f32_e32 v85, v85, v101
	v_cndmask_b32_e32 v105, v106, v105, vcc
	v_cndmask_b32_e64 v106, 0, v210, s[12:13]
	v_sub_f32_e32 v105, v105, v106
	v_exp_f32_e32 v106, v88
	v_mul_f32_e32 v85, 0xbfb8aa3b, v85
	v_exp_f32_e32 v85, v85
	v_add_f32_e32 v84, 1.0, v84
	v_rcp_f32_e32 v88, v84
	v_add_f32_e32 v84, 1.0, v106
	v_rcp_f32_e32 v106, v84
	v_add_f32_e32 v84, 1.0, v85
	v_add_f32_e32 v85, v89, v97
	v_mul_f32_e32 v85, 0xbfb8aa3b, v85
	v_add_f32_e32 v86, v86, v102
; __device__ __forceinline__ float bflo(unsigned w) { return __uint_as_float(w << 16); }
; __device__ __forceinline__ float bfhi(unsigned w) { return __uint_as_float(w & 0xffff0000u); }
; __device__ __forceinline__ float sigmoidf_(float x) { return __builtin_amdgcn_rcpf(1.0f + __expf(-x)); }
;     __device__ __forceinline__ void operator()(AccRef acc, const Unit& u, int wr, int wc, int fr, int fq) const {
;     ...
;             for (int j = 0; j < 4; ++j) k8[j] = -8.0f * __logf(1.0f + __expf(-l[j]));
; #pragma unroll
;             for (int ai = 0; ai < 2; ++ai)
; #pragma unroll
;                 for (int m = 0; m < 4; ++m) { const size_t off = (size_t)(row0 + ai * 128 + m * 16) * D + col0 + 4 * n;
;                     float lo[4], bo[4];
; #pragma unroll
;                     for (int j = 0; j < 4; ++j) { const unsigned w = rws[ai][m][2 * n + (j >> 1)]; const float rec = (j & 1) ? bfhi(w) : bflo(w);
;                         const float r = sigmoidf_(acc[ai][0][m][n][j] + ba[j]), ig = sigmoidf_(acc[ai][1][m][n][j] + bx[j]);
;                         const float la = k8[j] * r; const float mult = __builtin_sqrtf(1.0f - __expf(2.0f * la));
;                         lo[j] = la; bo[j] = mult * ig * rec; }
;                     *(u32x2*)(LA + off) = (u32x2){cvt_pk_bf16(lo[0], lo[1]), cvt_pk_bf16(lo[2], lo[3])}; *(u32x2*)(BV + off) = (u32x2){cvt_pk_bf16(bo[0], bo[1]), cvt_pk_bf16(bo[2], bo[3])}; }
	v_exp_f32_e32 v85, v85
	v_mul_f32_e32 v86, 0xbfb8aa3b, v86
	v_exp_f32_e32 v86, v86
	v_rcp_f32_e32 v89, v84
	v_add_f32_e32 v84, 1.0, v85
	v_add_f32_e32 v85, v90, v98
	v_rcp_f32_e32 v107, v84
	v_add_f32_e32 v84, 1.0, v86
	v_mul_f32_e32 v85, 0xbfb8aa3b, v85
	v_add_f32_e32 v86, v87, v103
	v_exp_f32_e32 v85, v85
	v_mul_f32_e32 v86, 0xbfb8aa3b, v86
	v_exp_f32_e32 v87, v86
	v_rcp_f32_e32 v86, v84
	v_add_f32_e32 v84, 1.0, v85
	v_rcp_f32_e32 v90, v84
	v_add_f32_e32 v84, 1.0, v87
	v_rcp_f32_e32 v87, v84
	v_pk_mul_f32 v[84:85], v[8:9], s[34:35] op_sel_hi:[1,0]
	v_add_f32_e32 v9, v91, v99
	v_pk_mul_f32 v[88:89], v[88:89], v[84:85]
	v_mul_f32_e32 v9, 0xbfb8aa3b, v9
	v_add_f32_e32 v8, v88, v88
	v_mul_f32_e32 v8, 0x3fb8aa3b, v8
	v_exp_f32_e32 v8, v8
	v_exp_f32_e32 v9, v9
	v_add_f32_e32 v112, v89, v89
	v_mul_f32_e32 v112, 0x3fb8aa3b, v112
	v_sub_f32_e32 v8, 1.0, v8
	v_add_f32_e32 v9, 1.0, v9
	v_exp_f32_e32 v112, v112
	v_sqrt_f32_e32 v110, v8
	v_rcp_f32_e32 v91, v9
	v_cvt_pk_bf16_f32 v88, v88, v89
	v_add_f32_e32 v72, v72, v100
	v_add_u32_e32 v9, -1, v110
	v_fma_f32 v111, -v9, v110, v8
	v_cmp_ge_f32_e64 s[12:13], 0, v111
	v_add_u32_e32 v111, 1, v110
	v_mul_f32_e32 v72, 0xbfb8aa3b, v72
	v_cndmask_b32_e64 v9, v110, v9, s[12:13]
	v_fma_f32 v110, -v111, v110, v8
	v_cmp_lt_f32_e64 s[12:13], 0, v110
	v_exp_f32_e32 v72, v72
	v_add_f32_e32 v73, v73, v101
	v_cndmask_b32_e64 v9, v9, v111, s[12:13]
	v_sub_f32_e32 v111, 1.0, v112
	v_sqrt_f32_e32 v112, v111
	v_add_f32_e32 v72, 1.0, v72
	v_rcp_f32_e32 v72, v72
	v_mov_b32_e32 v110, v9
	v_add_u32_e32 v8, -1, v112
	v_fma_f32 v9, -v8, v112, v111
	v_cmp_ge_f32_e32 vcc, 0, v9
	v_add_u32_e32 v114, 1, v112
	v_mul_f32_e32 v73, 0xbfb8aa3b, v73
	v_cndmask_b32_e32 v113, v112, v8, vcc
	v_pk_mul_f32 v[8:9], v[104:105], s[34:35] op_sel_hi:[1,0]
	v_fma_f32 v112, -v114, v112, v111
	v_pk_mul_f32 v[86:87], v[86:87], v[8:9]
	v_cmp_lt_f32_e32 vcc, 0, v112
	v_add_f32_e32 v104, v86, v86
	v_mul_f32_e32 v104, 0x3fb8aa3b, v104
	v_exp_f32_e32 v104, v104
	v_cndmask_b32_e32 v105, v113, v114, vcc
	v_sub_f32_e32 v104, 1.0, v104
	v_add_f32_e32 v113, v87, v87
	v_mul_f32_e32 v113, 0x3fb8aa3b, v113
	v_sqrt_f32_e32 v112, v104
	v_exp_f32_e32 v113, v113
	v_exp_f32_e32 v73, v73
	v_add_u32_e32 v89, -1, v112
	v_mov_b32_e32 v111, v105
	v_fma_f32 v105, -v89, v112, v104
	v_cmp_ge_f32_e64 s[12:13], 0, v105
	v_add_u32_e32 v105, 1, v112
	v_pk_mul_f32 v[106:107], v[106:107], v[110:111]
	v_cndmask_b32_e64 v89, v112, v89, s[12:13]
	v_fma_f32 v112, -v105, v112, v104
	v_cmp_lt_f32_e64 s[12:13], 0, v112
	v_sub_f32_e32 v112, 1.0, v113
	s_nop 0
	v_cndmask_b32_e64 v89, v89, v105, s[12:13]
	v_sqrt_f32_e32 v113, v112
	v_add_f32_e32 v76, v76, v96
	v_add_f32_e32 v73, 1.0, v73
	v_mov_b32_e32 v104, v89
	v_add_u32_e32 v89, -1, v113
	v_fma_f32 v105, -v89, v113, v112
	v_cmp_ge_f32_e32 vcc, 0, v105
	v_add_u32_e32 v105, 1, v113
	v_mul_f32_e32 v76, 0xbfb8aa3b, v76
	v_cndmask_b32_e32 v89, v113, v89, vcc
	v_fma_f32 v113, -v105, v113, v112
	v_cmp_lt_f32_e32 vcc, 0, v113
	v_rcp_f32_e32 v73, v73
	v_exp_f32_e32 v76, v76
	v_cndmask_b32_e32 v89, v89, v105, vcc
	v_add_f32_e32 v77, v77, v97
	v_add_f32_e32 v74, v74, v102
	v_mov_b32_e32 v105, v89
	v_cvt_pk_bf16_f32 v89, v86, v87
	v_lshlrev_b64 v[86:87], 1, v[108:109]
	v_lshl_add_u64 v[108:109], s[70:71], 0, v[86:87]
	global_store_dwordx2 v[108:109], v[88:89], off
	v_lshlrev_b32_e32 v88, 16, v94
	v_and_b32_e32 v89, 0xffff0000, v94
	v_lshlrev_b32_e32 v94, 16, v95
	v_and_b32_e32 v95, 0xffff0000, v95
	v_pk_mul_f32 v[90:91], v[90:91], v[104:105]
	v_pk_mul_f32 v[88:89], v[106:107], v[88:89]
	v_pk_mul_f32 v[90:91], v[90:91], v[94:95]
	v_cvt_pk_bf16_f32 v88, v88, v89
	v_cvt_pk_bf16_f32 v89, v90, v91
	v_mul_f32_e32 v90, v72, v84
	v_add_f32_e32 v72, v90, v90
	v_mul_f32_e32 v72, 0x3fb8aa3b, v72
	v_exp_f32_e32 v72, v72
	v_lshl_add_u64 v[86:87], s[68:69], 0, v[86:87]
	global_store_dwordx2 v[86:87], v[88:89], off
	v_mul_f32_e32 v88, v73, v85
	v_sub_f32_e32 v72, 1.0, v72
	v_add_f32_e32 v73, v88, v88
	v_mul_f32_e32 v73, 0x3fb8aa3b, v73
	v_mov_b32_e32 v91, v72
	v_sqrt_f32_e32 v94, v91
	v_add_f32_e32 v72, 1.0, v76
	v_exp_f32_e32 v73, v73
	v_mul_f32_e32 v77, 0xbfb8aa3b, v77
	v_add_u32_e32 v76, -1, v94
	v_fma_f32 v86, -v76, v94, v91
	v_cmp_ge_f32_e64 s[12:13], 0, v86
	v_add_u32_e32 v86, 1, v94
	v_fma_f32 v87, -v86, v94, v91
	v_cndmask_b32_e64 v76, v94, v76, s[12:13]
	v_cmp_lt_f32_e64 s[12:13], 0, v87
	v_sub_f32_e32 v73, 1.0, v73
	v_mul_f32_e32 v74, 0xbfb8aa3b, v74
	v_cndmask_b32_e64 v76, v76, v86, s[12:13]
	v_exp_f32_e32 v77, v77
	v_exp_f32_e32 v74, v74
	v_mov_b32_e32 v86, v73
	v_sqrt_f32_e32 v87, v86
	v_add_f32_e32 v73, 1.0, v77
	v_add_f32_e32 v74, 1.0, v74
	v_add_u32_e32 v77, -1, v87
	v_fma_f32 v89, -v77, v87, v86
	v_rcp_f32_e32 v74, v74
	v_cmp_ge_f32_e64 s[12:13], 0, v89
	v_add_u32_e32 v89, 1, v87
	v_add_f32_e32 v75, v75, v103
	v_cndmask_b32_e64 v77, v87, v77, s[12:13]
	v_fma_f32 v87, -v89, v87, v86
	v_cmp_lt_f32_e64 s[12:13], 0, v87
	v_add_f32_e32 v78, v78, v98
	v_mul_f32_e32 v75, 0xbfb8aa3b, v75
	v_cndmask_b32_e64 v77, v77, v89, s[12:13]
	v_mul_f32_e32 v89, v74, v8
	v_add_f32_e32 v74, v89, v89
	v_mul_f32_e32 v74, 0x3fb8aa3b, v74
	v_exp_f32_e32 v74, v74
	v_mul_f32_e32 v78, 0xbfb8aa3b, v78
	v_sub_f32_e32 v74, 1.0, v74
	v_exp_f32_e32 v75, v75
	v_exp_f32_e32 v78, v78
	v_mov_b32_e32 v87, v74
	v_sqrt_f32_e32 v91, v87
	v_add_f32_e32 v75, 1.0, v75
	v_add_f32_e32 v74, 1.0, v78
	v_add_u32_e32 v78, -1, v91
	v_rcp_f32_e32 v75, v75
	v_fma_f32 v86, -v78, v91, v87
	v_cmp_ge_f32_e64 s[12:13], 0, v86
	v_add_u32_e32 v86, 1, v91
	v_add_f32_e32 v79, v79, v99
	v_cndmask_b32_e64 v78, v91, v78, s[12:13]
	v_fma_f32 v91, -v86, v91, v87
	v_cmp_lt_f32_e64 s[12:13], 0, v91
; __device__ __forceinline__ float bflo(unsigned w) { return __uint_as_float(w << 16); }
; __device__ __forceinline__ float bfhi(unsigned w) { return __uint_as_float(w & 0xffff0000u); }
; __device__ __forceinline__ float sigmoidf_(float x) { return __builtin_amdgcn_rcpf(1.0f + __expf(-x)); }
;     __device__ __forceinline__ void operator()(AccRef acc, const Unit& u, int wr, int wc, int fr, int fq) const {
;     ...
;             for (int ai = 0; ai < 2; ++ai)
; #pragma unroll
;                 for (int m = 0; m < 4; ++m) { const size_t off = (size_t)(row0 + ai * 128 + m * 16) * D + col0 + 4 * n;
;                     float lo[4], bo[4];
; #pragma unroll
;                     for (int j = 0; j < 4; ++j) { const unsigned w = rws[ai][m][2 * n + (j >> 1)]; const float rec = (j & 1) ? bfhi(w) : bflo(w);
;                         const float r = sigmoidf_(acc[ai][0][m][n][j] + ba[j]), ig = sigmoidf_(acc[ai][1][m][n][j] + bx[j]);
;                         const float la = k8[j] * r; const float mult = __builtin_sqrtf(1.0f - __expf(2.0f * la));
;                         lo[j] = la; bo[j] = mult * ig * rec; }
;                     *(u32x2*)(LA + off) = (u32x2){cvt_pk_bf16(lo[0], lo[1]), cvt_pk_bf16(lo[2], lo[3])}; *(u32x2*)(BV + off) = (u32x2){cvt_pk_bf16(bo[0], bo[1]), cvt_pk_bf16(bo[2], bo[3])}; }
	v_mul_f32_e32 v91, v75, v9
	v_add_f32_e32 v75, v91, v91
	v_mul_f32_e32 v75, 0x3fb8aa3b, v75
	v_exp_f32_e32 v75, v75
	v_cndmask_b32_e64 v78, v78, v86, s[12:13]
	v_sub_f32_e32 v75, 1.0, v75
	v_mul_f32_e32 v79, 0xbfb8aa3b, v79
	v_exp_f32_e32 v79, v79
	v_mov_b32_e32 v86, v75
	v_sqrt_f32_e32 v94, v86
	v_add_f32_e32 v60, v60, v100
	v_add_f32_e32 v75, 1.0, v79
	v_add_u32_e32 v79, -1, v94
	v_mul_f32_e32 v60, 0xbfb8aa3b, v60
	v_fma_f32 v87, -v79, v94, v86
	v_exp_f32_e32 v60, v60
	v_cmp_ge_f32_e64 s[12:13], 0, v87
	v_add_u32_e32 v87, 1, v94
	v_rcp_f32_e32 v72, v72
	v_cndmask_b32_e64 v79, v94, v79, s[12:13]
	v_fma_f32 v94, -v87, v94, v86
	v_cmp_lt_f32_e64 s[12:13], 0, v94
	v_rcp_f32_e32 v73, v73
	v_rcp_f32_e32 v74, v74
	v_rcp_f32_e32 v75, v75
	v_cndmask_b32_e64 v79, v79, v87, s[12:13]
	v_add_f32_e32 v60, 1.0, v60
	v_rcp_f32_e32 v60, v60
	v_pk_mul_f32 v[72:73], v[72:73], v[76:77]
	v_lshlrev_b32_e32 v76, 16, v83
	v_and_b32_e32 v77, 0xffff0000, v83
	v_pk_mul_f32 v[74:75], v[74:75], v[78:79]
	v_add_f32_e32 v61, v61, v101
	v_pk_mul_f32 v[74:75], v[74:75], v[76:77]
	v_mul_f32_e32 v76, v60, v84
	v_add_f32_e32 v60, v76, v76
	v_mul_f32_e32 v60, 0x3fb8aa3b, v60
	v_exp_f32_e32 v60, v60
	v_mul_f32_e32 v61, 0xbfb8aa3b, v61
	v_exp_f32_e32 v61, v61
	v_lshl_add_u64 v[86:87], v[92:93], 0, v[180:181]
	v_sub_f32_e32 v60, 1.0, v60
	v_lshlrev_b64 v[86:87], 1, v[86:87]
	v_add_f32_e32 v64, v64, v96
	v_add_f32_e32 v61, 1.0, v61
	v_cvt_pk_bf16_f32 v88, v90, v88
	v_cvt_pk_bf16_f32 v89, v89, v91
	v_lshl_add_u64 v[90:91], s[70:71], 0, v[86:87]
	v_mul_f32_e32 v64, 0xbfb8aa3b, v64
	v_mov_b32_e32 v77, v60
	v_rcp_f32_e32 v61, v61
	global_store_dwordx2 v[90:91], v[88:89], off
	v_lshlrev_b32_e32 v88, 16, v82
	v_and_b32_e32 v89, 0xffff0000, v82
	v_exp_f32_e32 v64, v64
	v_sqrt_f32_e32 v78, v77
	v_pk_mul_f32 v[72:73], v[72:73], v[88:89]
	v_add_f32_e32 v65, v65, v97
	v_cvt_pk_bf16_f32 v72, v72, v73
	v_cvt_pk_bf16_f32 v73, v74, v75
	v_lshl_add_u64 v[74:75], s[68:69], 0, v[86:87]
	global_store_dwordx2 v[74:75], v[72:73], off
	v_mul_f32_e32 v74, v61, v85
	v_add_f32_e32 v60, 1.0, v64
	v_add_u32_e32 v64, -1, v78
	v_add_f32_e32 v61, v74, v74
	v_fma_f32 v72, -v64, v78, v77
	v_mul_f32_e32 v61, 0x3fb8aa3b, v61
	v_cmp_ge_f32_e64 s[12:13], 0, v72
	v_add_u32_e32 v72, 1, v78
	v_exp_f32_e32 v61, v61
	v_fma_f32 v73, -v72, v78, v77
	v_cndmask_b32_e64 v64, v78, v64, s[12:13]
	v_cmp_lt_f32_e64 s[12:13], 0, v73
	v_sub_f32_e32 v61, 1.0, v61
	v_add_f32_e32 v62, v62, v102
	v_cndmask_b32_e64 v64, v64, v72, s[12:13]
	v_mul_f32_e32 v65, 0xbfb8aa3b, v65
	v_mul_f32_e32 v62, 0xbfb8aa3b, v62
	v_mov_b32_e32 v72, v61
	v_exp_f32_e32 v65, v65
	v_sqrt_f32_e32 v73, v72
	v_exp_f32_e32 v62, v62
	v_add_f32_e32 v61, 1.0, v65
	v_add_u32_e32 v65, -1, v73
	v_add_f32_e32 v62, 1.0, v62
	v_fma_f32 v75, -v65, v73, v72
	v_rcp_f32_e32 v62, v62
	v_cmp_ge_f32_e64 s[12:13], 0, v75
	v_add_u32_e32 v75, 1, v73
	v_add_f32_e32 v63, v63, v103
	v_cndmask_b32_e64 v65, v73, v65, s[12:13]
	v_fma_f32 v73, -v75, v73, v72
	v_cmp_lt_f32_e64 s[12:13], 0, v73
	v_add_f32_e32 v66, v66, v98
	v_mul_f32_e32 v63, 0xbfb8aa3b, v63
	v_cndmask_b32_e64 v65, v65, v75, s[12:13]
	v_mul_f32_e32 v75, v62, v8
	v_add_f32_e32 v62, v75, v75
	v_mul_f32_e32 v62, 0x3fb8aa3b, v62
	v_exp_f32_e32 v62, v62
	v_mul_f32_e32 v66, 0xbfb8aa3b, v66
	v_sub_f32_e32 v62, 1.0, v62
	v_exp_f32_e32 v63, v63
	v_exp_f32_e32 v66, v66
	v_mov_b32_e32 v73, v62
	v_sqrt_f32_e32 v77, v73
	v_add_f32_e32 v63, 1.0, v63
	v_add_f32_e32 v62, 1.0, v66
	v_add_u32_e32 v66, -1, v77
	v_rcp_f32_e32 v63, v63
	v_fma_f32 v72, -v66, v77, v73
	v_cmp_ge_f32_e64 s[12:13], 0, v72
	v_add_u32_e32 v72, 1, v77
	v_add_f32_e32 v67, v67, v99
	v_cndmask_b32_e64 v66, v77, v66, s[12:13]
	v_fma_f32 v77, -v72, v77, v73
	v_cmp_lt_f32_e64 s[12:13], 0, v77
	v_mul_f32_e32 v77, v63, v9
	v_add_f32_e32 v63, v77, v77
	v_mul_f32_e32 v63, 0x3fb8aa3b, v63
	v_exp_f32_e32 v63, v63
	v_cndmask_b32_e64 v66, v66, v72, s[12:13]
	v_sub_f32_e32 v63, 1.0, v63
	v_mul_f32_e32 v67, 0xbfb8aa3b, v67
	v_exp_f32_e32 v67, v67
	v_mov_b32_e32 v72, v63
	v_sqrt_f32_e32 v78, v72
	v_add_f32_e32 v48, v48, v100
	v_add_f32_e32 v63, 1.0, v67
	v_add_u32_e32 v67, -1, v78
	v_mul_f32_e32 v48, 0xbfb8aa3b, v48
	v_fma_f32 v73, -v67, v78, v72
	v_exp_f32_e32 v48, v48
	v_cmp_ge_f32_e64 s[12:13], 0, v73
	v_add_u32_e32 v73, 1, v78
	v_rcp_f32_e32 v60, v60
	v_cndmask_b32_e64 v67, v78, v67, s[12:13]
	v_fma_f32 v78, -v73, v78, v72
	v_cmp_lt_f32_e64 s[12:13], 0, v78
	v_rcp_f32_e32 v61, v61
	v_rcp_f32_e32 v62, v62
	v_rcp_f32_e32 v63, v63
	v_cndmask_b32_e64 v67, v67, v73, s[12:13]
	v_add_f32_e32 v48, 1.0, v48
	v_rcp_f32_e32 v48, v48
	v_pk_mul_f32 v[60:61], v[60:61], v[64:65]
	v_lshlrev_b32_e32 v64, 16, v71
	v_and_b32_e32 v65, 0xffff0000, v71
	v_pk_mul_f32 v[62:63], v[62:63], v[66:67]
	v_add_f32_e32 v49, v49, v101
	v_pk_mul_f32 v[62:63], v[62:63], v[64:65]
	v_mul_f32_e32 v64, v48, v84
	v_add_f32_e32 v48, v64, v64
	v_mul_f32_e32 v48, 0x3fb8aa3b, v48
	v_exp_f32_e32 v48, v48
	v_mul_f32_e32 v49, 0xbfb8aa3b, v49
	v_exp_f32_e32 v49, v49
	v_lshl_add_u64 v[72:73], v[80:81], 0, v[180:181]
	v_sub_f32_e32 v48, 1.0, v48
	v_lshlrev_b64 v[72:73], 1, v[72:73]
	v_add_f32_e32 v52, v52, v96
	v_add_f32_e32 v49, 1.0, v49
	v_cvt_pk_bf16_f32 v74, v76, v74
	v_cvt_pk_bf16_f32 v75, v75, v77
	v_lshl_add_u64 v[76:77], s[70:71], 0, v[72:73]
	v_mul_f32_e32 v52, 0xbfb8aa3b, v52
	v_mov_b32_e32 v65, v48
	v_rcp_f32_e32 v49, v49
	global_store_dwordx2 v[76:77], v[74:75], off
	v_lshlrev_b32_e32 v74, 16, v70
	v_and_b32_e32 v75, 0xffff0000, v70
	v_exp_f32_e32 v52, v52
	v_sqrt_f32_e32 v66, v65
	v_pk_mul_f32 v[60:61], v[60:61], v[74:75]
	v_add_f32_e32 v53, v53, v97
	v_cvt_pk_bf16_f32 v60, v60, v61
	v_cvt_pk_bf16_f32 v61, v62, v63
; __device__ __forceinline__ float bflo(unsigned w) { return __uint_as_float(w << 16); }
; __device__ __forceinline__ float bfhi(unsigned w) { return __uint_as_float(w & 0xffff0000u); }
; __device__ __forceinline__ float sigmoidf_(float x) { return __builtin_amdgcn_rcpf(1.0f + __expf(-x)); }
;     __device__ __forceinline__ void operator()(AccRef acc, const Unit& u, int wr, int wc, int fr, int fq) const {
;     ...
;             for (int ai = 0; ai < 2; ++ai)
; #pragma unroll
;                 for (int m = 0; m < 4; ++m) { const size_t off = (size_t)(row0 + ai * 128 + m * 16) * D + col0 + 4 * n;
;                     float lo[4], bo[4];
; #pragma unroll
;                     for (int j = 0; j < 4; ++j) { const unsigned w = rws[ai][m][2 * n + (j >> 1)]; const float rec = (j & 1) ? bfhi(w) : bflo(w);
;                         const float r = sigmoidf_(acc[ai][0][m][n][j] + ba[j]), ig = sigmoidf_(acc[ai][1][m][n][j] + bx[j]);
;                         const float la = k8[j] * r; const float mult = __builtin_sqrtf(1.0f - __expf(2.0f * la));
;                         lo[j] = la; bo[j] = mult * ig * rec; }
;                     *(u32x2*)(LA + off) = (u32x2){cvt_pk_bf16(lo[0], lo[1]), cvt_pk_bf16(lo[2], lo[3])}; *(u32x2*)(BV + off) = (u32x2){cvt_pk_bf16(bo[0], bo[1]), cvt_pk_bf16(bo[2], bo[3])}; }
	v_lshl_add_u64 v[62:63], s[68:69], 0, v[72:73]
	global_store_dwordx2 v[62:63], v[60:61], off
	v_mul_f32_e32 v62, v49, v85
	v_add_f32_e32 v48, 1.0, v52
	v_add_u32_e32 v52, -1, v66
	v_add_f32_e32 v49, v62, v62
	v_fma_f32 v60, -v52, v66, v65
	v_mul_f32_e32 v49, 0x3fb8aa3b, v49
	v_cmp_ge_f32_e64 s[12:13], 0, v60
	v_add_u32_e32 v60, 1, v66
	v_exp_f32_e32 v49, v49
	v_fma_f32 v61, -v60, v66, v65
	v_cndmask_b32_e64 v52, v66, v52, s[12:13]
	v_cmp_lt_f32_e64 s[12:13], 0, v61
	v_sub_f32_e32 v49, 1.0, v49
	v_add_f32_e32 v50, v50, v102
	v_cndmask_b32_e64 v52, v52, v60, s[12:13]
	v_mul_f32_e32 v53, 0xbfb8aa3b, v53
	v_mul_f32_e32 v50, 0xbfb8aa3b, v50
	v_mov_b32_e32 v60, v49
	v_exp_f32_e32 v53, v53
	v_sqrt_f32_e32 v61, v60
	v_exp_f32_e32 v50, v50
	v_add_f32_e32 v49, 1.0, v53
	v_add_u32_e32 v53, -1, v61
	v_add_f32_e32 v50, 1.0, v50
	v_fma_f32 v63, -v53, v61, v60
	v_rcp_f32_e32 v50, v50
	v_cmp_ge_f32_e64 s[12:13], 0, v63
	v_add_u32_e32 v63, 1, v61
	v_add_f32_e32 v51, v51, v103
	v_cndmask_b32_e64 v53, v61, v53, s[12:13]
	v_fma_f32 v61, -v63, v61, v60
	v_cmp_lt_f32_e64 s[12:13], 0, v61
	v_add_f32_e32 v54, v54, v98
	v_mul_f32_e32 v51, 0xbfb8aa3b, v51
	v_cndmask_b32_e64 v53, v53, v63, s[12:13]
	v_mul_f32_e32 v63, v50, v8
	v_add_f32_e32 v50, v63, v63
	v_mul_f32_e32 v50, 0x3fb8aa3b, v50
	v_exp_f32_e32 v50, v50
	v_mul_f32_e32 v54, 0xbfb8aa3b, v54
	v_sub_f32_e32 v50, 1.0, v50
	v_exp_f32_e32 v51, v51
	v_exp_f32_e32 v54, v54
	v_mov_b32_e32 v61, v50
	v_sqrt_f32_e32 v65, v61
	v_add_f32_e32 v51, 1.0, v51
	v_add_f32_e32 v50, 1.0, v54
	v_add_u32_e32 v54, -1, v65
	v_rcp_f32_e32 v51, v51
	v_fma_f32 v60, -v54, v65, v61
	v_cmp_ge_f32_e64 s[12:13], 0, v60
	v_add_u32_e32 v60, 1, v65
	v_add_f32_e32 v55, v55, v99
	v_cndmask_b32_e64 v54, v65, v54, s[12:13]
	v_fma_f32 v65, -v60, v65, v61
	v_cmp_lt_f32_e64 s[12:13], 0, v65
	v_mul_f32_e32 v65, v51, v9
	v_add_f32_e32 v51, v65, v65
	v_mul_f32_e32 v51, 0x3fb8aa3b, v51
	v_exp_f32_e32 v51, v51
	v_cndmask_b32_e64 v54, v54, v60, s[12:13]
	v_sub_f32_e32 v51, 1.0, v51
	v_mul_f32_e32 v55, 0xbfb8aa3b, v55
	v_exp_f32_e32 v55, v55
	v_mov_b32_e32 v60, v51
	v_sqrt_f32_e32 v66, v60
	v_add_f32_e32 v36, v36, v100
	v_add_f32_e32 v51, 1.0, v55
	v_add_u32_e32 v55, -1, v66
	v_mul_f32_e32 v36, 0xbfb8aa3b, v36
	v_fma_f32 v61, -v55, v66, v60
	v_exp_f32_e32 v36, v36
	v_cmp_ge_f32_e64 s[12:13], 0, v61
	v_add_u32_e32 v61, 1, v66
	v_rcp_f32_e32 v48, v48
	v_cndmask_b32_e64 v55, v66, v55, s[12:13]
	v_fma_f32 v66, -v61, v66, v60
	v_cmp_lt_f32_e64 s[12:13], 0, v66
	v_rcp_f32_e32 v49, v49
	v_rcp_f32_e32 v50, v50
	v_rcp_f32_e32 v51, v51
	v_cndmask_b32_e64 v55, v55, v61, s[12:13]
	v_add_f32_e32 v36, 1.0, v36
	v_rcp_f32_e32 v36, v36
	v_pk_mul_f32 v[48:49], v[48:49], v[52:53]
	v_lshlrev_b32_e32 v52, 16, v59
	v_and_b32_e32 v53, 0xffff0000, v59
	v_pk_mul_f32 v[50:51], v[50:51], v[54:55]
	v_add_f32_e32 v37, v37, v101
	v_pk_mul_f32 v[50:51], v[50:51], v[52:53]
	v_mul_f32_e32 v52, v36, v84
	v_add_f32_e32 v36, v52, v52
	v_mul_f32_e32 v36, 0x3fb8aa3b, v36
	v_exp_f32_e32 v36, v36
	v_mul_f32_e32 v37, 0xbfb8aa3b, v37
	v_exp_f32_e32 v37, v37
	v_lshl_add_u64 v[60:61], v[68:69], 0, v[180:181]
	v_sub_f32_e32 v36, 1.0, v36
	v_lshlrev_b64 v[60:61], 1, v[60:61]
	v_add_f32_e32 v40, v40, v96
	v_add_f32_e32 v37, 1.0, v37
	v_cvt_pk_bf16_f32 v62, v64, v62
	v_cvt_pk_bf16_f32 v63, v63, v65
	v_lshl_add_u64 v[64:65], s[70:71], 0, v[60:61]
	v_mul_f32_e32 v40, 0xbfb8aa3b, v40
	v_mov_b32_e32 v53, v36
	v_rcp_f32_e32 v37, v37
	global_store_dwordx2 v[64:65], v[62:63], off
	v_lshlrev_b32_e32 v62, 16, v58
	v_and_b32_e32 v63, 0xffff0000, v58
	v_exp_f32_e32 v40, v40
	v_sqrt_f32_e32 v54, v53
	v_pk_mul_f32 v[48:49], v[48:49], v[62:63]
	v_add_f32_e32 v41, v41, v97
	v_cvt_pk_bf16_f32 v48, v48, v49
	v_cvt_pk_bf16_f32 v49, v50, v51
	v_lshl_add_u64 v[50:51], s[68:69], 0, v[60:61]
	global_store_dwordx2 v[50:51], v[48:49], off
	v_mul_f32_e32 v50, v37, v85
	v_add_f32_e32 v36, 1.0, v40
	v_add_u32_e32 v40, -1, v54
	v_add_f32_e32 v37, v50, v50
	v_fma_f32 v48, -v40, v54, v53
	v_mul_f32_e32 v37, 0x3fb8aa3b, v37
	v_cmp_ge_f32_e64 s[12:13], 0, v48
	v_add_u32_e32 v48, 1, v54
	v_exp_f32_e32 v37, v37
	v_fma_f32 v49, -v48, v54, v53
	v_cndmask_b32_e64 v40, v54, v40, s[12:13]
	v_cmp_lt_f32_e64 s[12:13], 0, v49
	v_sub_f32_e32 v37, 1.0, v37
	v_add_f32_e32 v38, v38, v102
	v_cndmask_b32_e64 v40, v40, v48, s[12:13]
	v_mul_f32_e32 v41, 0xbfb8aa3b, v41
	v_mul_f32_e32 v38, 0xbfb8aa3b, v38
	v_mov_b32_e32 v48, v37
	v_exp_f32_e32 v41, v41
	v_sqrt_f32_e32 v49, v48
	v_exp_f32_e32 v38, v38
	v_add_f32_e32 v37, 1.0, v41
	v_add_u32_e32 v41, -1, v49
	v_add_f32_e32 v38, 1.0, v38
	v_fma_f32 v51, -v41, v49, v48
	v_rcp_f32_e32 v38, v38
	v_cmp_ge_f32_e64 s[12:13], 0, v51
	v_add_u32_e32 v51, 1, v49
	v_add_f32_e32 v39, v39, v103
	v_cndmask_b32_e64 v41, v49, v41, s[12:13]
	v_fma_f32 v49, -v51, v49, v48
	v_cmp_lt_f32_e64 s[12:13], 0, v49
	v_add_f32_e32 v42, v42, v98
	v_mul_f32_e32 v39, 0xbfb8aa3b, v39
	v_cndmask_b32_e64 v41, v41, v51, s[12:13]
	v_mul_f32_e32 v51, v38, v8
	v_add_f32_e32 v38, v51, v51
	v_mul_f32_e32 v38, 0x3fb8aa3b, v38
	v_exp_f32_e32 v38, v38
	v_mul_f32_e32 v42, 0xbfb8aa3b, v42
	v_sub_f32_e32 v38, 1.0, v38
	v_exp_f32_e32 v39, v39
	v_exp_f32_e32 v42, v42
	v_mov_b32_e32 v49, v38
	v_sqrt_f32_e32 v53, v49
	v_add_f32_e32 v39, 1.0, v39
	v_add_f32_e32 v38, 1.0, v42
	v_add_u32_e32 v42, -1, v53
	v_rcp_f32_e32 v39, v39
	v_fma_f32 v48, -v42, v53, v49
	v_cmp_ge_f32_e64 s[12:13], 0, v48
	v_add_u32_e32 v48, 1, v53
	v_add_f32_e32 v43, v43, v99
	v_cndmask_b32_e64 v42, v53, v42, s[12:13]
	v_fma_f32 v53, -v48, v53, v49
	v_cmp_lt_f32_e64 s[12:13], 0, v53
	v_mul_f32_e32 v53, v39, v9
	v_add_f32_e32 v39, v53, v53
	v_mul_f32_e32 v39, 0x3fb8aa3b, v39
; __device__ __forceinline__ float bflo(unsigned w) { return __uint_as_float(w << 16); }
; __device__ __forceinline__ float bfhi(unsigned w) { return __uint_as_float(w & 0xffff0000u); }
; __device__ __forceinline__ float sigmoidf_(float x) { return __builtin_amdgcn_rcpf(1.0f + __expf(-x)); }
;     __device__ __forceinline__ void operator()(AccRef acc, const Unit& u, int wr, int wc, int fr, int fq) const {
;     ...
;             for (int ai = 0; ai < 2; ++ai)
; #pragma unroll
;                 for (int m = 0; m < 4; ++m) { const size_t off = (size_t)(row0 + ai * 128 + m * 16) * D + col0 + 4 * n;
;                     float lo[4], bo[4];
; #pragma unroll
;                     for (int j = 0; j < 4; ++j) { const unsigned w = rws[ai][m][2 * n + (j >> 1)]; const float rec = (j & 1) ? bfhi(w) : bflo(w);
;                         const float r = sigmoidf_(acc[ai][0][m][n][j] + ba[j]), ig = sigmoidf_(acc[ai][1][m][n][j] + bx[j]);
;                         const float la = k8[j] * r; const float mult = __builtin_sqrtf(1.0f - __expf(2.0f * la));
;                         lo[j] = la; bo[j] = mult * ig * rec; }
;                     *(u32x2*)(LA + off) = (u32x2){cvt_pk_bf16(lo[0], lo[1]), cvt_pk_bf16(lo[2], lo[3])}; *(u32x2*)(BV + off) = (u32x2){cvt_pk_bf16(bo[0], bo[1]), cvt_pk_bf16(bo[2], bo[3])}; }
	v_exp_f32_e32 v39, v39
	v_cndmask_b32_e64 v42, v42, v48, s[12:13]
	v_sub_f32_e32 v39, 1.0, v39
	v_mul_f32_e32 v43, 0xbfb8aa3b, v43
	v_exp_f32_e32 v43, v43
	v_mov_b32_e32 v48, v39
	v_sqrt_f32_e32 v54, v48
	v_add_f32_e32 v24, v24, v100
	v_add_f32_e32 v39, 1.0, v43
	v_add_u32_e32 v43, -1, v54
	v_mul_f32_e32 v24, 0xbfb8aa3b, v24
	v_fma_f32 v49, -v43, v54, v48
	v_exp_f32_e32 v24, v24
	v_cmp_ge_f32_e64 s[12:13], 0, v49
	v_add_u32_e32 v49, 1, v54
	v_rcp_f32_e32 v36, v36
	v_cndmask_b32_e64 v43, v54, v43, s[12:13]
	v_fma_f32 v54, -v49, v54, v48
	v_cmp_lt_f32_e64 s[12:13], 0, v54
	v_rcp_f32_e32 v37, v37
	v_rcp_f32_e32 v38, v38
	v_rcp_f32_e32 v39, v39
	v_cndmask_b32_e64 v43, v43, v49, s[12:13]
	v_add_f32_e32 v24, 1.0, v24
	v_rcp_f32_e32 v24, v24
	v_pk_mul_f32 v[36:37], v[36:37], v[40:41]
	v_lshlrev_b32_e32 v40, 16, v47
	v_and_b32_e32 v41, 0xffff0000, v47
	v_pk_mul_f32 v[38:39], v[38:39], v[42:43]
	v_add_f32_e32 v25, v25, v101
	v_pk_mul_f32 v[38:39], v[38:39], v[40:41]
	v_mul_f32_e32 v40, v24, v84
	v_add_f32_e32 v24, v40, v40
	v_mul_f32_e32 v24, 0x3fb8aa3b, v24
	v_exp_f32_e32 v24, v24
	v_mul_f32_e32 v25, 0xbfb8aa3b, v25
	v_exp_f32_e32 v25, v25
	v_lshl_add_u64 v[48:49], v[56:57], 0, v[180:181]
	v_sub_f32_e32 v24, 1.0, v24
	v_lshlrev_b64 v[48:49], 1, v[48:49]
	v_add_f32_e32 v28, v28, v96
	v_add_f32_e32 v25, 1.0, v25
	v_cvt_pk_bf16_f32 v50, v52, v50
	v_cvt_pk_bf16_f32 v51, v51, v53
	v_lshl_add_u64 v[52:53], s[70:71], 0, v[48:49]
	v_mul_f32_e32 v28, 0xbfb8aa3b, v28
	v_mov_b32_e32 v41, v24
	v_rcp_f32_e32 v25, v25
	global_store_dwordx2 v[52:53], v[50:51], off
	v_lshlrev_b32_e32 v50, 16, v46
	v_and_b32_e32 v51, 0xffff0000, v46
	v_exp_f32_e32 v28, v28
	v_sqrt_f32_e32 v42, v41
	v_pk_mul_f32 v[36:37], v[36:37], v[50:51]
	v_add_f32_e32 v29, v29, v97
	v_cvt_pk_bf16_f32 v36, v36, v37
	v_cvt_pk_bf16_f32 v37, v38, v39
	v_lshl_add_u64 v[38:39], s[68:69], 0, v[48:49]
	global_store_dwordx2 v[38:39], v[36:37], off
	v_mul_f32_e32 v38, v25, v85
	v_add_f32_e32 v24, 1.0, v28
	v_add_u32_e32 v28, -1, v42
	v_add_f32_e32 v25, v38, v38
	v_fma_f32 v36, -v28, v42, v41
	v_mul_f32_e32 v25, 0x3fb8aa3b, v25
	v_cmp_ge_f32_e64 s[12:13], 0, v36
	v_add_u32_e32 v36, 1, v42
	v_exp_f32_e32 v25, v25
	v_fma_f32 v37, -v36, v42, v41
	v_cndmask_b32_e64 v28, v42, v28, s[12:13]
	v_cmp_lt_f32_e64 s[12:13], 0, v37
	v_sub_f32_e32 v25, 1.0, v25
	v_add_f32_e32 v26, v26, v102
	v_cndmask_b32_e64 v28, v28, v36, s[12:13]
	v_mul_f32_e32 v29, 0xbfb8aa3b, v29
	v_mul_f32_e32 v26, 0xbfb8aa3b, v26
	v_mov_b32_e32 v36, v25
	v_exp_f32_e32 v29, v29
	v_sqrt_f32_e32 v37, v36
	v_exp_f32_e32 v26, v26
	v_add_f32_e32 v25, 1.0, v29
	v_add_u32_e32 v29, -1, v37
	v_add_f32_e32 v26, 1.0, v26
	v_fma_f32 v39, -v29, v37, v36
	v_rcp_f32_e32 v26, v26
	v_cmp_ge_f32_e64 s[12:13], 0, v39
	v_add_u32_e32 v39, 1, v37
	v_add_f32_e32 v27, v27, v103
	v_cndmask_b32_e64 v29, v37, v29, s[12:13]
	v_fma_f32 v37, -v39, v37, v36
	v_cmp_lt_f32_e64 s[12:13], 0, v37
	v_add_f32_e32 v30, v30, v98
	v_mul_f32_e32 v27, 0xbfb8aa3b, v27
	v_cndmask_b32_e64 v29, v29, v39, s[12:13]
	v_mul_f32_e32 v39, v26, v8
	v_add_f32_e32 v26, v39, v39
	v_mul_f32_e32 v26, 0x3fb8aa3b, v26
	v_exp_f32_e32 v26, v26
	v_mul_f32_e32 v30, 0xbfb8aa3b, v30
	v_sub_f32_e32 v26, 1.0, v26
	v_exp_f32_e32 v27, v27
	v_exp_f32_e32 v30, v30
	v_mov_b32_e32 v37, v26
	v_sqrt_f32_e32 v41, v37
	v_add_f32_e32 v27, 1.0, v27
	v_add_f32_e32 v26, 1.0, v30
	v_add_u32_e32 v30, -1, v41
	v_rcp_f32_e32 v27, v27
	v_fma_f32 v36, -v30, v41, v37
	v_cmp_ge_f32_e64 s[12:13], 0, v36
	v_add_u32_e32 v36, 1, v41
	v_add_f32_e32 v31, v31, v99
	v_cndmask_b32_e64 v30, v41, v30, s[12:13]
	v_fma_f32 v41, -v36, v41, v37
	v_cmp_lt_f32_e64 s[12:13], 0, v41
	v_mul_f32_e32 v41, v27, v9
	v_add_f32_e32 v27, v41, v41
	v_mul_f32_e32 v27, 0x3fb8aa3b, v27
	v_exp_f32_e32 v27, v27
	v_cndmask_b32_e64 v30, v30, v36, s[12:13]
	v_sub_f32_e32 v27, 1.0, v27
	v_mul_f32_e32 v31, 0xbfb8aa3b, v31
	v_exp_f32_e32 v31, v31
	v_mov_b32_e32 v36, v27
	v_sqrt_f32_e32 v42, v36
	v_add_f32_e32 v12, v12, v100
	v_add_f32_e32 v27, 1.0, v31
	v_add_u32_e32 v31, -1, v42
	v_mul_f32_e32 v12, 0xbfb8aa3b, v12
	v_fma_f32 v37, -v31, v42, v36
	v_exp_f32_e32 v12, v12
	v_cmp_ge_f32_e64 s[12:13], 0, v37
	v_add_u32_e32 v37, 1, v42
	v_rcp_f32_e32 v24, v24
	v_cndmask_b32_e64 v31, v42, v31, s[12:13]
	v_fma_f32 v42, -v37, v42, v36
	v_cmp_lt_f32_e64 s[12:13], 0, v42
	v_rcp_f32_e32 v25, v25
	v_rcp_f32_e32 v26, v26
	v_rcp_f32_e32 v27, v27
	v_cndmask_b32_e64 v31, v31, v37, s[12:13]
	v_add_f32_e32 v12, 1.0, v12
	v_rcp_f32_e32 v12, v12
	v_pk_mul_f32 v[24:25], v[24:25], v[28:29]
	v_lshlrev_b32_e32 v28, 16, v35
	v_and_b32_e32 v29, 0xffff0000, v35
	v_pk_mul_f32 v[26:27], v[26:27], v[30:31]
	v_add_f32_e32 v13, v13, v101
	v_pk_mul_f32 v[26:27], v[26:27], v[28:29]
	v_mul_f32_e32 v28, v12, v84
	v_add_f32_e32 v12, v28, v28
	v_mul_f32_e32 v12, 0x3fb8aa3b, v12
	v_exp_f32_e32 v12, v12
	v_mul_f32_e32 v13, 0xbfb8aa3b, v13
	v_exp_f32_e32 v13, v13
	v_lshl_add_u64 v[36:37], v[44:45], 0, v[180:181]
	v_sub_f32_e32 v12, 1.0, v12
	v_lshlrev_b64 v[36:37], 1, v[36:37]
	v_add_f32_e32 v16, v16, v96
	v_add_f32_e32 v13, 1.0, v13
	v_cvt_pk_bf16_f32 v38, v40, v38
	v_cvt_pk_bf16_f32 v39, v39, v41
	v_lshl_add_u64 v[40:41], s[70:71], 0, v[36:37]
	v_mul_f32_e32 v16, 0xbfb8aa3b, v16
	v_mov_b32_e32 v29, v12
	v_rcp_f32_e32 v13, v13
	global_store_dwordx2 v[40:41], v[38:39], off
	v_lshlrev_b32_e32 v38, 16, v34
	v_and_b32_e32 v39, 0xffff0000, v34
	v_exp_f32_e32 v16, v16
	v_sqrt_f32_e32 v30, v29
	v_pk_mul_f32 v[24:25], v[24:25], v[38:39]
	v_add_f32_e32 v17, v17, v97
	v_cvt_pk_bf16_f32 v24, v24, v25
	v_cvt_pk_bf16_f32 v25, v26, v27
	v_lshl_add_u64 v[26:27], s[68:69], 0, v[36:37]
	global_store_dwordx2 v[26:27], v[24:25], off
; __device__ __forceinline__ float bflo(unsigned w) { return __uint_as_float(w << 16); }
; __device__ __forceinline__ float bfhi(unsigned w) { return __uint_as_float(w & 0xffff0000u); }
; __device__ __forceinline__ float sigmoidf_(float x) { return __builtin_amdgcn_rcpf(1.0f + __expf(-x)); }
;     __device__ __forceinline__ void operator()(AccRef acc, const Unit& u, int wr, int wc, int fr, int fq) const {
;     ...
;             for (int ai = 0; ai < 2; ++ai)
; #pragma unroll
;                 for (int m = 0; m < 4; ++m) { const size_t off = (size_t)(row0 + ai * 128 + m * 16) * D + col0 + 4 * n;
;                     float lo[4], bo[4];
; #pragma unroll
;                     for (int j = 0; j < 4; ++j) { const unsigned w = rws[ai][m][2 * n + (j >> 1)]; const float rec = (j & 1) ? bfhi(w) : bflo(w);
;                         const float r = sigmoidf_(acc[ai][0][m][n][j] + ba[j]), ig = sigmoidf_(acc[ai][1][m][n][j] + bx[j]);
;                         const float la = k8[j] * r; const float mult = __builtin_sqrtf(1.0f - __expf(2.0f * la));
;                         lo[j] = la; bo[j] = mult * ig * rec; }
;                     *(u32x2*)(LA + off) = (u32x2){cvt_pk_bf16(lo[0], lo[1]), cvt_pk_bf16(lo[2], lo[3])}; *(u32x2*)(BV + off) = (u32x2){cvt_pk_bf16(bo[0], bo[1]), cvt_pk_bf16(bo[2], bo[3])}; }
	v_mul_f32_e32 v26, v13, v85
	v_add_f32_e32 v12, 1.0, v16
	v_add_u32_e32 v16, -1, v30
	v_add_f32_e32 v13, v26, v26
	v_fma_f32 v24, -v16, v30, v29
	v_mul_f32_e32 v13, 0x3fb8aa3b, v13
	v_cmp_ge_f32_e64 s[12:13], 0, v24
	v_add_u32_e32 v24, 1, v30
	v_exp_f32_e32 v13, v13
	v_fma_f32 v25, -v24, v30, v29
	v_cndmask_b32_e64 v16, v30, v16, s[12:13]
	v_cmp_lt_f32_e64 s[12:13], 0, v25
	v_sub_f32_e32 v13, 1.0, v13
	v_add_f32_e32 v14, v14, v102
	v_cndmask_b32_e64 v16, v16, v24, s[12:13]
	v_mul_f32_e32 v17, 0xbfb8aa3b, v17
	v_mul_f32_e32 v14, 0xbfb8aa3b, v14
	v_mov_b32_e32 v24, v13
	v_exp_f32_e32 v17, v17
	v_sqrt_f32_e32 v25, v24
	v_exp_f32_e32 v14, v14
	v_add_f32_e32 v13, 1.0, v17
	v_add_u32_e32 v17, -1, v25
	v_add_f32_e32 v14, 1.0, v14
	v_fma_f32 v27, -v17, v25, v24
	v_rcp_f32_e32 v14, v14
	v_cmp_ge_f32_e64 s[12:13], 0, v27
	v_add_u32_e32 v27, 1, v25
	v_add_f32_e32 v15, v15, v103
	v_cndmask_b32_e64 v17, v25, v17, s[12:13]
	v_fma_f32 v25, -v27, v25, v24
	v_cmp_lt_f32_e64 s[12:13], 0, v25
	v_add_f32_e32 v18, v18, v98
	v_mul_f32_e32 v15, 0xbfb8aa3b, v15
	v_cndmask_b32_e64 v17, v17, v27, s[12:13]
	v_mul_f32_e32 v27, v14, v8
	v_add_f32_e32 v14, v27, v27
	v_mul_f32_e32 v14, 0x3fb8aa3b, v14
	v_exp_f32_e32 v14, v14
	v_mul_f32_e32 v18, 0xbfb8aa3b, v18
	v_sub_f32_e32 v14, 1.0, v14
	v_exp_f32_e32 v15, v15
	v_exp_f32_e32 v18, v18
	v_mov_b32_e32 v25, v14
	v_sqrt_f32_e32 v29, v25
	v_add_f32_e32 v15, 1.0, v15
	v_add_f32_e32 v14, 1.0, v18
	v_add_u32_e32 v18, -1, v29
	v_rcp_f32_e32 v15, v15
	v_fma_f32 v24, -v18, v29, v25
	v_cmp_ge_f32_e64 s[12:13], 0, v24
	v_add_u32_e32 v24, 1, v29
	v_add_f32_e32 v19, v19, v99
	v_cndmask_b32_e64 v18, v29, v18, s[12:13]
	v_fma_f32 v29, -v24, v29, v25
	v_cmp_lt_f32_e64 s[12:13], 0, v29
	v_mul_f32_e32 v29, v15, v9
	v_add_f32_e32 v15, v29, v29
	v_mul_f32_e32 v15, 0x3fb8aa3b, v15
	v_exp_f32_e32 v15, v15
	v_cndmask_b32_e64 v18, v18, v24, s[12:13]
	v_sub_f32_e32 v15, 1.0, v15
	v_mul_f32_e32 v19, 0xbfb8aa3b, v19
	v_exp_f32_e32 v19, v19
	v_mov_b32_e32 v24, v15
	v_sqrt_f32_e32 v30, v24
	v_add_f32_e32 v0, v0, v100
	v_add_f32_e32 v15, 1.0, v19
	v_add_u32_e32 v19, -1, v30
	v_mul_f32_e32 v0, 0xbfb8aa3b, v0
	v_fma_f32 v25, -v19, v30, v24
	v_exp_f32_e32 v0, v0
	v_cmp_ge_f32_e64 s[12:13], 0, v25
	v_add_u32_e32 v25, 1, v30
	v_rcp_f32_e32 v12, v12
	v_cndmask_b32_e64 v19, v30, v19, s[12:13]
	v_fma_f32 v30, -v25, v30, v24
	v_cmp_lt_f32_e64 s[12:13], 0, v30
	v_rcp_f32_e32 v13, v13
	v_rcp_f32_e32 v14, v14
	v_rcp_f32_e32 v15, v15
	v_cndmask_b32_e64 v19, v19, v25, s[12:13]
	v_add_f32_e32 v0, 1.0, v0
	v_rcp_f32_e32 v0, v0
	v_pk_mul_f32 v[12:13], v[12:13], v[16:17]
	v_lshlrev_b32_e32 v16, 16, v23
	v_and_b32_e32 v17, 0xffff0000, v23
	v_pk_mul_f32 v[14:15], v[14:15], v[18:19]
	v_add_f32_e32 v4, v4, v96
	v_pk_mul_f32 v[14:15], v[14:15], v[16:17]
	v_mul_f32_e32 v16, v0, v84
	v_add_f32_e32 v0, v16, v16
	v_mul_f32_e32 v0, 0x3fb8aa3b, v0
	v_exp_f32_e32 v0, v0
	v_lshl_add_u64 v[24:25], v[32:33], 0, v[180:181]
	v_mul_f32_e32 v4, 0xbfb8aa3b, v4
	v_lshlrev_b64 v[24:25], 1, v[24:25]
	v_sub_f32_e32 v0, 1.0, v0
	v_exp_f32_e32 v4, v4
	v_add_f32_e32 v1, v1, v101
	v_mov_b32_e32 v17, v0
	v_sqrt_f32_e32 v18, v17
	v_cvt_pk_bf16_f32 v26, v28, v26
	v_cvt_pk_bf16_f32 v27, v27, v29
	v_lshl_add_u64 v[28:29], s[70:71], 0, v[24:25]
	v_mul_f32_e32 v1, 0xbfb8aa3b, v1
	global_store_dwordx2 v[28:29], v[26:27], off
	v_lshlrev_b32_e32 v26, 16, v22
	v_and_b32_e32 v27, 0xffff0000, v22
	v_exp_f32_e32 v1, v1
	v_pk_mul_f32 v[12:13], v[12:13], v[26:27]
	v_add_f32_e32 v0, 1.0, v4
	v_cvt_pk_bf16_f32 v12, v12, v13
	v_cvt_pk_bf16_f32 v13, v14, v15
	v_lshl_add_u64 v[14:15], s[68:69], 0, v[24:25]
	v_add_u32_e32 v4, -1, v18
	global_store_dwordx2 v[14:15], v[12:13], off
	v_fma_f32 v12, -v4, v18, v17
	v_cmp_ge_f32_e64 s[12:13], 0, v12
	v_add_u32_e32 v12, 1, v18
	v_add_f32_e32 v1, 1.0, v1
	v_fma_f32 v13, -v12, v18, v17
	v_rcp_f32_e32 v1, v1
	v_cndmask_b32_e64 v4, v18, v4, s[12:13]
	v_cmp_lt_f32_e64 s[12:13], 0, v13
	v_add_f32_e32 v5, v5, v97
	v_mul_f32_e32 v5, 0xbfb8aa3b, v5
	v_cndmask_b32_e64 v4, v4, v12, s[12:13]
	v_mul_f32_e32 v12, v1, v85
	v_add_f32_e32 v1, v12, v12
	v_mul_f32_e32 v1, 0x3fb8aa3b, v1
	v_exp_f32_e32 v1, v1
	v_exp_f32_e32 v5, v5
	v_add_f32_e32 v2, v2, v102
	v_mul_f32_e32 v2, 0xbfb8aa3b, v2
	v_sub_f32_e32 v1, 1.0, v1
	v_exp_f32_e32 v2, v2
	v_mov_b32_e32 v13, v1
	v_sqrt_f32_e32 v14, v13
	v_add_f32_e32 v1, 1.0, v5
	v_add_f32_e32 v2, 1.0, v2
	v_add_u32_e32 v5, -1, v14
	v_fma_f32 v15, -v5, v14, v13
	v_cmp_ge_f32_e64 s[12:13], 0, v15
	v_add_u32_e32 v15, 1, v14
	v_rcp_f32_e32 v2, v2
	v_cndmask_b32_e64 v5, v14, v5, s[12:13]
	v_fma_f32 v14, -v15, v14, v13
	v_cmp_lt_f32_e64 s[12:13], 0, v14
	v_add_f32_e32 v6, v6, v98
	v_mul_f32_e32 v6, 0xbfb8aa3b, v6
	v_cndmask_b32_e64 v5, v5, v15, s[12:13]
	v_mul_f32_e32 v14, v2, v8
	v_add_f32_e32 v2, v14, v14
	v_mul_f32_e32 v2, 0x3fb8aa3b, v2
	v_exp_f32_e32 v2, v2
	v_exp_f32_e32 v6, v6
	v_add_f32_e32 v3, v3, v103
	v_mul_f32_e32 v3, 0xbfb8aa3b, v3
	v_sub_f32_e32 v2, 1.0, v2
	v_exp_f32_e32 v3, v3
	v_mov_b32_e32 v8, v2
	v_sqrt_f32_e32 v15, v8
	v_add_f32_e32 v2, 1.0, v6
	v_add_f32_e32 v3, 1.0, v3
	v_add_u32_e32 v6, -1, v15
	v_fma_f32 v13, -v6, v15, v8
	v_cmp_ge_f32_e64 s[12:13], 0, v13
	v_add_u32_e32 v13, 1, v15
	v_rcp_f32_e32 v3, v3
	v_cndmask_b32_e64 v6, v15, v6, s[12:13]
	v_fma_f32 v15, -v13, v15, v8
	v_cmp_lt_f32_e64 s[12:13], 0, v15
	v_add_f32_e32 v7, v7, v99
	v_mul_f32_e32 v7, 0xbfb8aa3b, v7
	v_cndmask_b32_e64 v6, v6, v13, s[12:13]
	v_mul_f32_e32 v13, v3, v9
	v_add_f32_e32 v3, v13, v13
	v_mul_f32_e32 v3, 0x3fb8aa3b, v3
	v_exp_f32_e32 v3, v3
	v_exp_f32_e32 v7, v7
	v_rcp_f32_e32 v0, v0
	v_sub_f32_e32 v3, 1.0, v3
	v_rcp_f32_e32 v1, v1
	v_mov_b32_e32 v9, v3
	v_sqrt_f32_e32 v15, v9
	v_add_f32_e32 v3, 1.0, v7
	v_rcp_f32_e32 v2, v2
	v_rcp_f32_e32 v3, v3
	v_add_u32_e32 v7, -1, v15
	v_fma_f32 v8, -v7, v15, v9
	v_cmp_ge_f32_e64 s[12:13], 0, v8
	v_add_u32_e32 v8, 1, v15
	v_cvt_pk_bf16_f32 v12, v16, v12
	v_cndmask_b32_e64 v7, v15, v7, s[12:13]
	v_fma_f32 v15, -v8, v15, v9
	v_cmp_lt_f32_e64 s[12:13], 0, v15
	v_cvt_pk_bf16_f32 v13, v14, v13
	v_pk_mul_f32 v[0:1], v[0:1], v[4:5]
	v_cndmask_b32_e64 v7, v7, v8, s[12:13]
	v_lshlrev_b32_e32 v4, 16, v11
	v_and_b32_e32 v5, 0xffff0000, v11
	v_lshl_add_u64 v[8:9], v[20:21], 0, v[180:181]
	v_lshlrev_b64 v[8:9], 1, v[8:9]
	v_lshl_add_u64 v[14:15], s[70:71], 0, v[8:9]
	global_store_dwordx2 v[14:15], v[12:13], off
	v_lshlrev_b32_e32 v12, 16, v10
	v_and_b32_e32 v13, 0xffff0000, v10
	v_pk_mul_f32 v[2:3], v[2:3], v[6:7]
	v_pk_mul_f32 v[0:1], v[0:1], v[12:13]
	v_pk_mul_f32 v[2:3], v[2:3], v[4:5]
	v_cvt_pk_bf16_f32 v0, v0, v1
	v_cvt_pk_bf16_f32 v1, v2, v3
	v_lshl_add_u64 v[2:3], s[68:69], 0, v[8:9]
	s_andn2_b64 vcc, exec, s[10:11]
	s_mov_b32 s13, s38
	s_mov_b32 s12, s40
	s_mov_b64 s[14:15], s[42:43]
	global_store_dwordx2 v[2:3], v[0:1], off
	s_cbranch_vccz .LBB0_1100
